# P6 wait placement + hoisted loop-invariant gain loads in row passes P0/P4/P8/P10 (no more store-drain waits)
# speedup vs baseline: 1.0251x; 1.0251x over previous
; template <int RB, int XB>
; __device__ __forceinline__ void row_op2(const RowPtrs (&r)[NR], bool has_src, const float* gpost, const float* gnext, int lane) {
;     ...
;         for (int o = 1; o < 64; o <<= 1) {
; #pragma unroll
;             for (int k = 0; k < NR; ++k) ss[k] += __shfl_xor(ss[k], o); }
; #pragma unroll
;         for (int k = 0; k < NR; ++k) { const float rs = rsqrtf(ss[k] * (1.f / D) + EPS);
; #pragma unroll
;             for (int j = 0; j < 4; ++j) { const f32x4 g = ((const f32x4*)gnext)[lane + 64 * j]; const f32x4 h = x[k][j] * rs * g;
; __global__ void __launch_bounds__(512, 2) fwd_kernel(Args args) {
;     ...
;         for (int m0 = gw; m0 < T; m0 += NR * NGW) { RowPtrs r[NR];
; #pragma unroll
;             for (int k = 0; k < NR; ++k) { const int m = (m0 + k * NGW < T) ? m0 + k * NGW : m0; r[k] = RowPtrs{nullptr, nullptr, XROW(m), nullptr, H + (size_t)m * D, false}; }
;             row_op2<0, 0>(r, false, nullptr, args.in[I_GMIXPRE], lane); }
.LBB0_29:
	s_cmpk_gt_i32 s34, 0x41ff
	s_cbranch_scc1 .LBB0_46
	v_mov_b32_e32 v1, 0
	v_lshlrev_b32_e32 v0, 4, v128
	s_waitcnt lgkmcnt(0)
	v_lshl_add_u64 v[36:37], s[28:29], 0, v[0:1]
	v_lshlrev_b32_e32 v0, 3, v128
	v_lshl_add_u64 v[38:39], s[52:53], 0, v[0:1]
	v_mbcnt_lo_u32_b32 v0, -1, 0
	v_mbcnt_hi_u32_b32 v42, -1, v0
	s_cmp_lg_u64 s[28:29], 0
	v_and_b32_e32 v0, 64, v42
	s_cselect_b64 s[6:7], -1, 0
	s_mov_b32 s9, 0
	v_lshlrev_b32_e32 v41, 4, v128
	v_mov_b32_e32 v40, 0x358637bd
	s_mov_b32 s10, 0x3a800000
	s_mov_b32 s3, 0x800000
	v_add_u32_e32 v43, 64, v0
	v_xor_b32_e32 v44, 1, v42
	v_xor_b32_e32 v45, 2, v42
	v_xor_b32_e32 v46, 4, v42
	v_xor_b32_e32 v47, 8, v42
	v_xor_b32_e32 v48, 16, v42
	v_xor_b32_e32 v49, 32, v42
	s_mov_b32 s30, s34
	global_load_dwordx4 v[240:243], v[36:37], off
	global_load_dwordx4 v[244:247], v[36:37], off offset:1024
	global_load_dwordx4 v[248:251], v[36:37], off offset:2048
	global_load_dwordx4 v[252:255], v[36:37], off offset:3072
	s_branch .LBB0_32

; __device__ __forceinline__ float bf2f(unsigned b) { return __uint_as_float(b << 16); }
; __device__ __forceinline__ unsigned pk2(float lo, float hi) { unsigned r; asm("v_cvt_pk_bf16_f32 %0, %1, %2" : "=v"(r) : "v"(lo), "v"(hi)); return r; }
; template <int RB, int XB>
; __device__ __forceinline__ void row_op2(const RowPtrs (&r)[NR], bool has_src, const float* gpost, const float* gnext, int lane) {
;     ...
; #pragma unroll
;     for (int k = 0; k < NR; ++k)
; #pragma unroll
;         for (int j = 0; j < 4; ++j) {
;             if (RB) { const u32x2 wv = ((const u32x2*)r[k].resid)[lane + 64 * j]; x[k][j] = (f32x4){bf2f(wv.x & 0xffffu), bf2f(wv.x >> 16), bf2f(wv.y & 0xffffu), bf2f(wv.y >> 16)}; }
;             else x[k][j] = ((const f32x4*)r[k].resid)[lane + 64 * j]; }
;     ...
;     if (gnext != nullptr) {
;         float ss[NR];
; #pragma unroll
;         for (int k = 0; k < NR; ++k) { ss[k] = 0.f;
; #pragma unroll
;             for (int j = 0; j < 4; ++j) ss[k] += (x[k][j].x * x[k][j].x + x[k][j].y * x[k][j].y) + (x[k][j].z * x[k][j].z + x[k][j].w * x[k][j].w); }
; #pragma unroll
;         for (int o = 1; o < 64; o <<= 1) {
; #pragma unroll
;             for (int k = 0; k < NR; ++k) ss[k] += __shfl_xor(ss[k], o); }
; #pragma unroll
;         for (int k = 0; k < NR; ++k) { const float rs = rsqrtf(ss[k] * (1.f / D) + EPS);
; #pragma unroll
;             for (int j = 0; j < 4; ++j) { const f32x4 g = ((const f32x4*)gnext)[lane + 64 * j]; const f32x4 h = x[k][j] * rs * g;
;                 u32x2 w; w.x = pk2(h.x, h.y); w.y = pk2(h.z, h.w); ((u32x2*)r[k].hout)[lane + 64 * j] = w; } }
.LBB0_45:
	global_load_dwordx4 v[20:23], v41, s[40:41]
	global_load_dwordx4 v[16:19], v41, s[40:41] offset:1024
	global_load_dwordx4 v[4:7], v41, s[40:41] offset:3072
	global_load_dwordx4 v[12:15], v41, s[40:41] offset:2048
	global_load_dwordx4 v[50:53], v[36:37], off
	v_cmp_lt_i32_e32 vcc, v44, v43
	s_lshl_b64 s[30:31], s[30:31], 11
	v_lshl_add_u64 v[66:67], v[38:39], 0, s[30:31]
	v_cndmask_b32_e32 v0, v42, v44, vcc
	v_lshlrev_b32_e32 v69, 2, v0
	v_cmp_lt_i32_e32 vcc, v45, v43
	s_lshl_b64 s[28:29], s[28:29], 11
	s_lshl_b64 s[12:13], s[12:13], 11
	s_waitcnt vmcnt(4)
	v_pk_mul_f32 v[0:1], v[22:23], v[22:23]
	v_pk_mul_f32 v[2:3], v[20:21], v[20:21]
	s_waitcnt vmcnt(3)
	v_pk_mul_f32 v[8:9], v[18:19], v[18:19]
	v_pk_mul_f32 v[10:11], v[16:17], v[16:17]
	v_pk_mov_b32 v[28:29], v[2:3], v[0:1] op_sel:[1,0]
	v_mov_b32_e32 v3, v1
	v_pk_mov_b32 v[0:1], v[10:11], v[8:9] op_sel:[1,0]
	v_mov_b32_e32 v11, v9
	s_waitcnt vmcnt(2)
	v_mul_f32_e32 v27, v4, v4
	s_waitcnt vmcnt(1)
	v_mul_f32_e32 v24, v13, v13
	v_mul_f32_e32 v26, v15, v15
	v_pk_add_f32 v[2:3], v[28:29], v[2:3]
	v_pk_add_f32 v[0:1], v[0:1], v[10:11]
	v_mul_f32_e32 v30, v5, v5
	v_mul_f32_e32 v31, v6, v6
	v_mul_f32_e32 v32, v7, v7
	v_pk_fma_f32 v[8:9], v[12:13], v[12:13], v[24:25] op_sel_hi:[1,1,0]
	v_pk_fma_f32 v[24:25], v[14:15], v[14:15], v[26:27] op_sel_hi:[1,1,0]
	v_pk_add_f32 v[2:3], v[2:3], v[2:3] op_sel:[0,1] op_sel_hi:[1,0]
	v_pk_add_f32 v[0:1], v[0:1], v[0:1] op_sel:[0,1] op_sel_hi:[1,0]
	v_mov_b32_e32 v9, v31
	v_mov_b32_e32 v25, v32
	v_mov_b32_e32 v3, v27
	v_mov_b32_e32 v1, v30
	v_pk_add_f32 v[8:9], v[8:9], v[24:25]
	v_pk_add_f32 v[0:1], v[2:3], v[0:1]
	v_cndmask_b32_e32 v2, v42, v45, vcc
	v_pk_add_f32 v[0:1], v[0:1], v[8:9]
	v_lshlrev_b32_e32 v81, 2, v2
	v_add_f32_e32 v0, v0, v1
	ds_bpermute_b32 v1, v69, v0
	v_cmp_lt_i32_e32 vcc, v46, v43
	s_waitcnt lgkmcnt(0)
	v_add_f32_e32 v0, v0, v1
	ds_bpermute_b32 v1, v81, v0
	v_cndmask_b32_e32 v2, v42, v46, vcc
	v_lshlrev_b32_e32 v84, 2, v2
	v_cmp_lt_i32_e32 vcc, v47, v43
	s_waitcnt lgkmcnt(0)
	v_add_f32_e32 v0, v0, v1
	ds_bpermute_b32 v1, v84, v0
	v_cndmask_b32_e32 v2, v42, v47, vcc
	v_lshlrev_b32_e32 v85, 2, v2
	v_cmp_lt_i32_e32 vcc, v48, v43
	s_waitcnt lgkmcnt(0)
	v_add_f32_e32 v0, v0, v1
	ds_bpermute_b32 v1, v85, v0
	v_cndmask_b32_e32 v2, v42, v48, vcc
	v_lshlrev_b32_e32 v86, 2, v2
	v_cmp_lt_i32_e32 vcc, v49, v43
	s_waitcnt lgkmcnt(0)
	v_add_f32_e32 v25, v0, v1
	ds_bpermute_b32 v26, v86, v25
	v_cndmask_b32_e32 v24, v42, v49, vcc
	v_lshlrev_b32_e32 v87, 2, v24
	global_load_dwordx4 v[0:3], v41, s[38:39] offset:3072
	global_load_dwordx4 v[8:11], v41, s[38:39] offset:2048
	s_waitcnt lgkmcnt(0)
	v_add_f32_e32 v58, v25, v26
	ds_bpermute_b32 v59, v87, v58
	global_load_dwordx4 v[24:27], v41, s[38:39] offset:1024
	global_load_dwordx4 v[28:31], v41, s[38:39]
	global_load_dwordx4 v[32:35], v41, s[36:37] offset:3072
	global_load_dwordx4 v[54:57], v41, s[36:37] offset:2048
	s_waitcnt lgkmcnt(0)
	v_add_f32_e32 v58, v58, v59
	v_fmamk_f32 v58, v58, 0x3a800000, v40
	v_mul_f32_e32 v59, 0x4b800000, v58
	v_cmp_gt_f32_e32 vcc, s3, v58
	s_waitcnt vmcnt(5)
	v_mul_f32_e32 v90, v2, v2
	v_cndmask_b32_e32 v58, v58, v59, vcc
	v_rsq_f32_e32 v68, v58
	global_load_dwordx4 v[58:61], v41, s[36:37] offset:1024
	global_load_dwordx4 v[62:65], v41, s[36:37]
	s_waitcnt vmcnt(5)
	v_pk_mul_f32 v[72:73], v[24:25], v[24:25]
	s_waitcnt vmcnt(2)
	v_mul_f32_e32 v74, v55, v55
	v_mul_f32_e32 v70, 0x45800000, v68
	v_cndmask_b32_e32 v68, v68, v70, vcc
	v_pk_mul_f32 v[20:21], v[20:21], v[68:69] op_sel_hi:[1,0]
	v_pk_mul_f32 v[22:23], v[22:23], v[68:69] op_sel_hi:[1,0]
	v_pk_mul_f32 v[20:21], v[50:51], v[20:21]
	v_pk_mul_f32 v[22:23], v[52:53], v[22:23]
	v_cvt_pk_bf16_f32 v20, v20, v21
	v_pk_mul_f32 v[16:17], v[16:17], v[68:69] op_sel_hi:[1,0]
	v_cvt_pk_bf16_f32 v21, v22, v23
	global_store_dwordx2 v[66:67], v[20:21], off
	s_nop 0
	v_pk_mul_f32 v[18:19], v[18:19], v[68:69] op_sel_hi:[1,0]
	v_pk_mul_f32 v[12:13], v[12:13], v[68:69] op_sel_hi:[1,0]
	v_pk_mul_f32 v[14:15], v[14:15], v[68:69] op_sel_hi:[1,0]
	v_pk_mul_f32 v[4:5], v[4:5], v[68:69] op_sel_hi:[1,0]
	v_pk_mul_f32 v[6:7], v[6:7], v[68:69] op_sel_hi:[1,0]
	v_pk_mul_f32 v[50:51], v[30:31], v[30:31]
	v_pk_mul_f32 v[52:53], v[28:29], v[28:29]
	v_pk_mul_f32 v[70:71], v[26:27], v[26:27]
	v_mul_f32_e32 v76, v57, v57
	v_mul_f32_e32 v78, v9, v9
	v_mul_f32_e32 v80, v11, v11
	v_mul_f32_e32 v88, v34, v34
	v_mul_f32_e32 v89, v35, v35
	v_mul_f32_e32 v91, v3, v3
	v_mul_f32_e32 v92, v32, v32
	v_mul_f32_e32 v93, v33, v33
	v_mul_f32_e32 v94, v0, v0
	v_mul_f32_e32 v95, v1, v1
	s_waitcnt vmcnt(1)
; __device__ __forceinline__ unsigned pk2(float lo, float hi) { unsigned r; asm("v_cvt_pk_bf16_f32 %0, %1, %2" : "=v"(r) : "v"(lo), "v"(hi)); return r; }
; template <int RB, int XB>
; __device__ __forceinline__ void row_op2(const RowPtrs (&r)[NR], bool has_src, const float* gpost, const float* gnext, int lane) {
;     ...
;         for (int k = 0; k < NR; ++k) { ss[k] = 0.f;
; #pragma unroll
;             for (int j = 0; j < 4; ++j) ss[k] += (x[k][j].x * x[k][j].x + x[k][j].y * x[k][j].y) + (x[k][j].z * x[k][j].z + x[k][j].w * x[k][j].w); }
; #pragma unroll
;         for (int o = 1; o < 64; o <<= 1) {
; #pragma unroll
;             for (int k = 0; k < NR; ++k) ss[k] += __shfl_xor(ss[k], o); }
; #pragma unroll
;         for (int k = 0; k < NR; ++k) { const float rs = rsqrtf(ss[k] * (1.f / D) + EPS);
; #pragma unroll
;             for (int j = 0; j < 4; ++j) { const f32x4 g = ((const f32x4*)gnext)[lane + 64 * j]; const f32x4 h = x[k][j] * rs * g;
;                 u32x2 w; w.x = pk2(h.x, h.y); w.y = pk2(h.z, h.w); ((u32x2*)r[k].hout)[lane + 64 * j] = w; } }
	v_pk_mul_f32 v[16:17], v[244:245], v[16:17]
	v_pk_mul_f32 v[18:19], v[246:247], v[18:19]
	v_cvt_pk_bf16_f32 v16, v16, v17
	v_pk_mul_f32 v[20:21], v[60:61], v[60:61]
	v_cvt_pk_bf16_f32 v17, v18, v19
	global_store_dwordx2 v[66:67], v[16:17], off offset:512
	s_nop 0
	v_pk_mul_f32 v[22:23], v[58:59], v[58:59]
	s_nop 0
	v_pk_mul_f32 v[12:13], v[248:249], v[12:13]
	v_pk_mul_f32 v[14:15], v[250:251], v[14:15]
	v_cvt_pk_bf16_f32 v12, v12, v13
	v_pk_mul_f32 v[16:17], v[64:65], v[64:65]
	v_cvt_pk_bf16_f32 v13, v14, v15
	global_store_dwordx2 v[66:67], v[12:13], off offset:1024
	s_nop 0
	v_pk_mul_f32 v[18:19], v[62:63], v[62:63]
	s_nop 0
	v_pk_mul_f32 v[4:5], v[4:5], v[252:253]
	v_pk_mul_f32 v[6:7], v[6:7], v[254:255]
	v_cvt_pk_bf16_f32 v4, v4, v5
	v_pk_mov_b32 v[82:83], v[18:19], v[16:17] op_sel:[1,0]
	v_cvt_pk_bf16_f32 v5, v6, v7
	global_store_dwordx2 v[66:67], v[4:5], off offset:1536
	s_nop 0
	v_mov_b32_e32 v19, v17
	v_pk_mov_b32 v[16:17], v[22:23], v[20:21] op_sel:[1,0]
	v_mov_b32_e32 v23, v21
	v_pk_mov_b32 v[20:21], v[52:53], v[50:51] op_sel:[1,0]
	v_mov_b32_e32 v53, v51
	v_pk_mov_b32 v[50:51], v[72:73], v[70:71] op_sel:[1,0]
	v_mov_b32_e32 v73, v71
	v_pk_add_f32 v[18:19], v[82:83], v[18:19]
	v_pk_add_f32 v[12:13], v[16:17], v[22:23]
	v_pk_add_f32 v[14:15], v[20:21], v[52:53]
	v_pk_add_f32 v[16:17], v[50:51], v[72:73]
	v_pk_fma_f32 v[70:71], v[54:55], v[54:55], v[74:75] op_sel_hi:[1,1,0]
	v_pk_fma_f32 v[74:75], v[56:57], v[56:57], v[76:77] op_sel_hi:[1,1,0]
	v_pk_fma_f32 v[76:77], v[8:9], v[8:9], v[78:79] op_sel_hi:[1,1,0]
	v_pk_fma_f32 v[78:79], v[10:11], v[10:11], v[80:81] op_sel_hi:[1,1,0]
	v_pk_add_f32 v[18:19], v[18:19], v[18:19] op_sel:[0,1] op_sel_hi:[1,0]
	v_pk_add_f32 v[12:13], v[12:13], v[12:13] op_sel:[0,1] op_sel_hi:[1,0]
	v_pk_add_f32 v[14:15], v[14:15], v[14:15] op_sel:[0,1] op_sel_hi:[1,0]
	v_pk_add_f32 v[16:17], v[16:17], v[16:17] op_sel:[0,1] op_sel_hi:[1,0]
	v_mov_b32_e32 v71, v88
	v_mov_b32_e32 v75, v89
	v_mov_b32_e32 v77, v90
	v_mov_b32_e32 v79, v91
	v_mov_b32_e32 v19, v92
	v_mov_b32_e32 v13, v93
	v_mov_b32_e32 v15, v94
	v_mov_b32_e32 v17, v95
	v_pk_add_f32 v[20:21], v[70:71], v[74:75]
	v_pk_add_f32 v[22:23], v[76:77], v[78:79]
	v_pk_add_f32 v[12:13], v[18:19], v[12:13]
	v_pk_add_f32 v[14:15], v[14:15], v[16:17]
	v_pk_add_f32 v[12:13], v[12:13], v[20:21]
	v_pk_add_f32 v[14:15], v[14:15], v[22:23]
	v_mov_b32_e32 v17, v12
	v_mov_b32_e32 v16, v14
	v_mov_b32_e32 v12, v15
	v_pk_add_f32 v[12:13], v[16:17], v[12:13]
	ds_bpermute_b32 v15, v69, v13
	ds_bpermute_b32 v14, v69, v12
	s_waitcnt lgkmcnt(0)
	v_pk_add_f32 v[12:13], v[12:13], v[14:15]
	ds_bpermute_b32 v15, v81, v13
	ds_bpermute_b32 v14, v81, v12
	s_waitcnt lgkmcnt(0)
	v_pk_add_f32 v[12:13], v[12:13], v[14:15]
	ds_bpermute_b32 v15, v84, v13
	ds_bpermute_b32 v14, v84, v12
	s_waitcnt lgkmcnt(0)
	v_pk_add_f32 v[12:13], v[12:13], v[14:15]
	ds_bpermute_b32 v15, v85, v13
	ds_bpermute_b32 v14, v85, v12
	s_waitcnt lgkmcnt(0)
	v_pk_add_f32 v[12:13], v[12:13], v[14:15]
	ds_bpermute_b32 v15, v86, v13
	ds_bpermute_b32 v14, v86, v12
	s_waitcnt lgkmcnt(0)
	v_pk_add_f32 v[12:13], v[12:13], v[14:15]
	ds_bpermute_b32 v15, v87, v13
	ds_bpermute_b32 v14, v87, v12
	s_waitcnt lgkmcnt(0)
	v_pk_add_f32 v[12:13], v[12:13], v[14:15]
	s_nop 0
	v_pk_fma_f32 v[12:13], v[12:13], s[10:11], v[40:41] op_sel_hi:[1,0,0]
	s_nop 0
	v_mul_f32_e32 v14, 0x4b800000, v13
	v_cmp_gt_f32_e32 vcc, s3, v13
	s_nop 1
	v_cndmask_b32_e32 v13, v13, v14, vcc
	v_rsq_f32_e32 v13, v13
	v_lshl_add_u64 v[14:15], v[38:39], 0, s[28:29]
	v_mul_f32_e32 v16, 0x45800000, v13
	v_cndmask_b32_e32 v16, v13, v16, vcc
	v_pk_mul_f32 v[18:19], v[62:63], v[16:17] op_sel_hi:[1,0]
	v_pk_mul_f32 v[20:21], v[64:65], v[16:17] op_sel_hi:[1,0]
	s_nop 0
	v_pk_mul_f32 v[4:5], v[18:19], v[240:241]
	v_pk_mul_f32 v[6:7], v[20:21], v[242:243]
	v_cvt_pk_bf16_f32 v4, v4, v5
	v_pk_mul_f32 v[18:19], v[58:59], v[16:17] op_sel_hi:[1,0]
	v_cvt_pk_bf16_f32 v5, v6, v7
	global_store_dwordx2 v[14:15], v[4:5], off
	s_nop 0
	v_pk_mul_f32 v[20:21], v[60:61], v[16:17] op_sel_hi:[1,0]
	v_mul_f32_e32 v13, 0x4b800000, v12
	v_cmp_gt_f32_e32 vcc, s3, v12
	s_nop 0
	v_pk_mul_f32 v[4:5], v[18:19], v[244:245]
	v_pk_mul_f32 v[6:7], v[20:21], v[246:247]
	v_cvt_pk_bf16_f32 v4, v4, v5
	v_pk_mul_f32 v[18:19], v[54:55], v[16:17] op_sel_hi:[1,0]
	v_cvt_pk_bf16_f32 v5, v6, v7
	global_store_dwordx2 v[14:15], v[4:5], off offset:512
	s_nop 0
	v_pk_mul_f32 v[20:21], v[56:57], v[16:17] op_sel_hi:[1,0]
	v_cndmask_b32_e32 v12, v12, v13, vcc
	s_nop 0
	v_pk_mul_f32 v[4:5], v[18:19], v[248:249]
	v_pk_mul_f32 v[6:7], v[20:21], v[250:251]
	v_cvt_pk_bf16_f32 v4, v4, v5
	v_pk_mul_f32 v[18:19], v[32:33], v[16:17] op_sel_hi:[1,0]
	v_cvt_pk_bf16_f32 v5, v6, v7
	global_store_dwordx2 v[14:15], v[4:5], off offset:1024
	s_nop 0
	v_pk_mul_f32 v[16:17], v[34:35], v[16:17] op_sel_hi:[1,0]
	s_nop 0
	v_pk_mul_f32 v[4:5], v[18:19], v[252:253]
	v_pk_mul_f32 v[6:7], v[16:17], v[254:255]
	v_cvt_pk_bf16_f32 v4, v4, v5
	s_nop 0
	v_cvt_pk_bf16_f32 v5, v6, v7
	global_store_dwordx2 v[14:15], v[4:5], off offset:1536
	s_nop 0
	v_rsq_f32_e32 v14, v12
	v_lshl_add_u64 v[12:13], v[38:39], 0, s[12:13]
	v_mul_f32_e32 v15, 0x45800000, v14
	v_cndmask_b32_e32 v14, v14, v15, vcc
	v_pk_mul_f32 v[16:17], v[28:29], v[14:15] op_sel_hi:[1,0]
	v_pk_mul_f32 v[18:19], v[30:31], v[14:15] op_sel_hi:[1,0]
	v_pk_mul_f32 v[8:9], v[8:9], v[14:15] op_sel_hi:[1,0]
	v_pk_mul_f32 v[10:11], v[10:11], v[14:15] op_sel_hi:[1,0]
	v_pk_mul_f32 v[0:1], v[0:1], v[14:15] op_sel_hi:[1,0]
	v_pk_mul_f32 v[2:3], v[2:3], v[14:15] op_sel_hi:[1,0]
	s_nop 0
	v_pk_mul_f32 v[4:5], v[16:17], v[240:241]
	v_pk_mul_f32 v[6:7], v[18:19], v[242:243]
	v_cvt_pk_bf16_f32 v4, v4, v5
	v_pk_mul_f32 v[16:17], v[24:25], v[14:15] op_sel_hi:[1,0]
	v_cvt_pk_bf16_f32 v5, v6, v7
	global_store_dwordx2 v[12:13], v[4:5], off
	s_nop 0
	v_pk_mul_f32 v[18:19], v[26:27], v[14:15] op_sel_hi:[1,0]
	s_nop 0
	v_pk_mul_f32 v[4:5], v[16:17], v[244:245]
	v_pk_mul_f32 v[6:7], v[18:19], v[246:247]
	v_cvt_pk_bf16_f32 v4, v4, v5
	s_nop 0
	v_cvt_pk_bf16_f32 v5, v6, v7
	global_store_dwordx2 v[12:13], v[4:5], off offset:512
	s_nop 0
	s_nop 0
	v_pk_mul_f32 v[4:5], v[8:9], v[248:249]
	v_pk_mul_f32 v[6:7], v[10:11], v[250:251]
	v_cvt_pk_bf16_f32 v4, v4, v5
	s_nop 0
	v_cvt_pk_bf16_f32 v5, v6, v7
	global_store_dwordx2 v[12:13], v[4:5], off offset:1024
	s_nop 0
	s_nop 0
	v_pk_mul_f32 v[0:1], v[0:1], v[252:253]
	v_pk_mul_f32 v[2:3], v[2:3], v[254:255]
	v_cvt_pk_bf16_f32 v0, v0, v1
	s_nop 0
	v_cvt_pk_bf16_f32 v1, v2, v3
	global_store_dwordx2 v[12:13], v[0:1], off offset:1536
	s_branch .LBB0_31

; template <int RB, int XB>
; __device__ __forceinline__ void row_op2(const RowPtrs (&r)[NR], bool has_src, const float* gpost, const float* gnext, int lane) {
;     ...
;             for (int j = 0; j < 4; ++j) { const f32x4 g = ((const f32x4*)gnext)[lane + 64 * j]; const f32x4 h = x[k][j] * rs * g;
; __global__ void __launch_bounds__(512, 2) fwd_kernel(Args args) {
;     ...
;     if (IN(4)) {
;         for (int m0 = gw; m0 < T; m0 += NR * NGW) { RowPtrs r[NR];
; #pragma unroll
;             for (int k = 0; k < NR; ++k) { const int m = (m0 + k * NGW < T) ? m0 + k * NGW : m0;
;                 r[k] = RowPtrs{m < TP ? nullptr : FT3 + (size_t)(m - TP) * D, MIXB + (size_t)m * D, XROW(m), X1B + (size_t)m * D, H + (size_t)m * D, m >= TP}; }
;             row_op2<0, 1>(r, true, args.in[I_GMIXPOST], args.in[I_GFFNPRE], lane); }
.LBB0_528:
	s_cmp_lt_i32 s94, 5
	s_cselect_b64 s[6:7], -1, 0
	s_waitcnt lgkmcnt(0)
	s_and_b64 s[40:41], s[6:7], s[0:1]
	s_cmpk_lt_i32 s34, 0x4200
	s_cselect_b64 s[30:31], -1, 0
	s_and_b64 s[0:1], s[40:41], s[30:31]
	s_andn2_b64 vcc, exec, s[0:1]
	v_or_b32_e32 v130, 64, v128
	v_mbcnt_lo_u32_b32 v131, -1, 0
	v_lshlrev_b32_e32 v132, 4, v128
	s_mul_i32 s20, s14, 24
	v_lshlrev_b32_e32 v134, 3, v128
	s_cbranch_vccnz .LBB0_611
	v_mbcnt_hi_u32_b32 v0, -1, v131
	v_and_b32_e32 v1, 64, v0
	v_add_u32_e32 v1, 64, v1
	v_xor_b32_e32 v2, 1, v0
	v_cmp_lt_i32_e32 vcc, v2, v1
	v_readlane_b32 s60, v237, 0
	v_mov_b32_e32 v133, 0
	v_cndmask_b32_e32 v2, v0, v2, vcc
	v_lshlrev_b32_e32 v97, 2, v2
	v_xor_b32_e32 v2, 2, v0
	v_cmp_lt_i32_e32 vcc, v2, v1
	s_cmp_lg_u64 s[38:39], 0
	v_readlane_b32 s66, v237, 6
	v_cndmask_b32_e32 v2, v0, v2, vcc
	v_lshlrev_b32_e32 v99, 2, v2
	v_xor_b32_e32 v2, 4, v0
	v_cmp_lt_i32_e32 vcc, v2, v1
	v_readlane_b32 s67, v237, 7
	v_lshl_add_u64 v[100:101], s[36:37], 0, v[132:133]
	v_cndmask_b32_e32 v2, v0, v2, vcc
	v_lshlrev_b32_e32 v109, 2, v2
	v_xor_b32_e32 v2, 8, v0
	s_cselect_b64 s[36:37], -1, 0
	s_cmp_lg_u64 s[66:67], 0
	v_cmp_lt_i32_e32 vcc, v2, v1
	v_lshl_add_u64 v[102:103], s[38:39], 0, v[132:133]
	s_cselect_b64 s[38:39], -1, 0
	s_ashr_i32 s35, s34, 31
	v_cndmask_b32_e32 v2, v0, v2, vcc
	s_lshl_b64 s[0:1], s[34:35], 11
	v_lshlrev_b32_e32 v158, 2, v2
	v_xor_b32_e32 v2, 16, v0
	s_add_u32 s58, s92, s0
	v_cmp_lt_i32_e32 vcc, v2, v1
	v_readlane_b32 s61, v237, 1
	s_addc_u32 s59, s93, s1
	s_ashr_i32 s21, s20, 31
	v_cndmask_b32_e32 v2, v0, v2, vcc
	v_readlane_b32 s62, v237, 2
	s_lshl_b64 s[60:61], s[20:21], 11
	v_lshlrev_b32_e32 v159, 2, v2
	v_xor_b32_e32 v2, 32, v0
	v_readlane_b32 s63, v237, 3
	s_add_u32 s62, s66, s0
	v_cmp_lt_i32_e32 vcc, v2, v1
	s_addc_u32 s63, s67, s1
	s_lshl_b64 s[0:1], s[34:35], 12
	v_cndmask_b32_e32 v0, v0, v2, vcc
	v_readlane_b32 s64, v237, 4
	v_readlane_b32 s65, v237, 5
	v_mov_b32_e32 v135, v133
	s_add_u32 s3, s16, s0
	v_or_b32_e32 v96, 0x80, v128
	v_or_b32_e32 v98, 0xc0, v128
	s_mov_b32 s57, 0
	v_lshlrev_b32_e32 v160, 2, v0
	v_lshl_add_u64 v[104:105], s[66:67], 0, v[134:135]
	v_lshl_add_u64 v[106:107], s[52:53], 0, v[134:135]
	s_addc_u32 s33, s17, s1
	s_lshl_b64 s[64:65], s[20:21], 12
	v_lshlrev_b32_e32 v133, 4, v128
	v_mov_b32_e32 v108, 0x358637bd
	s_mov_b32 s66, 0x3a800000
	s_mov_b32 s21, 0x800000
	s_mov_b32 s0, s34
	global_load_dwordx4 v[240:243], v[102:103], off
	global_load_dwordx4 v[244:247], v[102:103], off offset:1024
	global_load_dwordx4 v[248:251], v[102:103], off offset:2048
	global_load_dwordx4 v[252:255], v[102:103], off offset:3072
	s_branch .LBB0_531

; __device__ __forceinline__ unsigned pk2(float lo, float hi) { unsigned r; asm("v_cvt_pk_bf16_f32 %0, %1, %2" : "=v"(r) : "v"(lo), "v"(hi)); return r; }
; template <int RB, int XB>
; __device__ __forceinline__ void row_op2(const RowPtrs (&r)[NR], bool has_src, const float* gpost, const float* gnext, int lane) {
;     ...
;     if (gnext != nullptr) {
;         float ss[NR];
; #pragma unroll
;         for (int k = 0; k < NR; ++k) { ss[k] = 0.f;
; #pragma unroll
;             for (int j = 0; j < 4; ++j) ss[k] += (x[k][j].x * x[k][j].x + x[k][j].y * x[k][j].y) + (x[k][j].z * x[k][j].z + x[k][j].w * x[k][j].w); }
; #pragma unroll
;         for (int o = 1; o < 64; o <<= 1) {
; #pragma unroll
;             for (int k = 0; k < NR; ++k) ss[k] += __shfl_xor(ss[k], o); }
; #pragma unroll
;         for (int k = 0; k < NR; ++k) { const float rs = rsqrtf(ss[k] * (1.f / D) + EPS);
; #pragma unroll
;             for (int j = 0; j < 4; ++j) { const f32x4 g = ((const f32x4*)gnext)[lane + 64 * j]; const f32x4 h = x[k][j] * rs * g;
;                 u32x2 w; w.x = pk2(h.x, h.y); w.y = pk2(h.z, h.w); ((u32x2*)r[k].hout)[lane + 64 * j] = w; } }
.LBB0_609:
	s_andn2_b64 vcc, exec, s[36:37]
	s_cbranch_vccnz .LBB0_530
	s_nop 0
	v_pk_mul_f32 v[52:53], v[46:47], v[46:47]
	v_pk_mul_f32 v[54:55], v[44:45], v[44:45]
	v_pk_mul_f32 v[56:57], v[42:43], v[42:43]
	v_pk_mul_f32 v[58:59], v[40:41], v[40:41]
	v_pk_mov_b32 v[64:65], v[54:55], v[52:53] op_sel:[1,0]
	v_mov_b32_e32 v55, v53
	v_pk_mov_b32 v[52:53], v[58:59], v[56:57] op_sel:[1,0]
	v_mov_b32_e32 v59, v57
	v_mul_f32_e32 v60, v36, v36
	v_mul_f32_e32 v62, v38, v38
	v_pk_add_f32 v[54:55], v[64:65], v[54:55]
	v_pk_add_f32 v[52:53], v[52:53], v[58:59]
	v_pk_fma_f32 v[56:57], v[36:37], v[36:37], v[60:61] op_sel_hi:[1,1,0]
	v_pk_fma_f32 v[60:61], v[38:39], v[38:39], v[62:63] op_sel_hi:[1,1,0]
	v_pk_add_f32 v[54:55], v[54:55], v[54:55] op_sel_hi:[0,1]
	v_pk_add_f32 v[52:53], v[52:53], v[52:53] op_sel_hi:[0,1]
	v_mul_f32_e32 v56, v32, v32
	v_mul_f32_e32 v60, v33, v33
	v_mul_f32_e32 v54, v34, v34
	v_mul_f32_e32 v52, v35, v35
	v_pk_add_f32 v[56:57], v[56:57], v[60:61]
	v_pk_add_f32 v[52:53], v[54:55], v[52:53]
	s_mov_b32 s0, 0x1c00000
	v_pk_add_f32 v[52:53], v[56:57], v[52:53]
	v_pk_mul_f32 v[56:57], v[14:15], v[14:15]
	v_add_f32_e32 v52, v52, v53
	ds_bpermute_b32 v53, v97, v52
	v_pk_mul_f32 v[58:59], v[12:13], v[12:13]
	v_pk_mul_f32 v[60:61], v[10:11], v[10:11]
	v_pk_mul_f32 v[62:63], v[8:9], v[8:9]
	v_mul_f32_e32 v64, v4, v4
	s_waitcnt lgkmcnt(0)
	v_add_f32_e32 v52, v52, v53
	ds_bpermute_b32 v53, v99, v52
	v_mul_f32_e32 v66, v6, v6
	s_waitcnt lgkmcnt(0)
	v_add_f32_e32 v52, v52, v53
	ds_bpermute_b32 v53, v109, v52
	s_waitcnt lgkmcnt(0)
	v_add_f32_e32 v52, v52, v53
	ds_bpermute_b32 v53, v158, v52
	s_waitcnt lgkmcnt(0)
	v_add_f32_e32 v52, v52, v53
	ds_bpermute_b32 v53, v159, v52
	s_waitcnt lgkmcnt(0)
	v_add_f32_e32 v52, v52, v53
	ds_bpermute_b32 v53, v160, v52
	s_waitcnt lgkmcnt(0)
	v_add_f32_e32 v52, v52, v53
	v_fmamk_f32 v52, v52, 0x3a800000, v108
	v_mul_f32_e32 v53, 0x4b800000, v52
	v_cmp_gt_f32_e32 vcc, s21, v52
	s_nop 1
	v_cndmask_b32_e32 v52, v52, v53, vcc
	v_rsq_f32_e32 v54, v52
	v_add_co_u32_e64 v52, s[0:1], s0, v110
	v_mul_f32_e32 v55, 0x45800000, v54
	v_cndmask_b32_e32 v54, v54, v55, vcc
	v_pk_mul_f32 v[44:45], v[44:45], v[54:55] op_sel_hi:[1,0]
	v_addc_co_u32_e64 v53, s[0:1], 0, v111, s[0:1]
	v_pk_mul_f32 v[46:47], v[46:47], v[54:55] op_sel_hi:[1,0]
	v_pk_mul_f32 v[40:41], v[40:41], v[54:55] op_sel_hi:[1,0]
	s_nop 0
	v_pk_mul_f32 v[44:45], v[240:241], v[44:45]
	v_pk_mul_f32 v[46:47], v[242:243], v[46:47]
	v_cvt_pk_bf16_f32 v44, v44, v45
	v_pk_mul_f32 v[42:43], v[42:43], v[54:55] op_sel_hi:[1,0]
	v_cvt_pk_bf16_f32 v45, v46, v47
	global_store_dwordx2 v[52:53], v[44:45], off
	s_nop 0
	v_pk_mul_f32 v[36:37], v[36:37], v[54:55] op_sel_hi:[1,0]
	v_pk_mul_f32 v[38:39], v[38:39], v[54:55] op_sel_hi:[1,0]
	v_pk_mul_f32 v[32:33], v[32:33], v[54:55] op_sel_hi:[1,0]
	v_pk_mul_f32 v[34:35], v[34:35], v[54:55] op_sel_hi:[1,0]
	v_mul_f32_e32 v48, v20, v20
	v_mul_f32_e32 v50, v22, v22
	s_nop 0
	v_pk_mul_f32 v[40:41], v[244:245], v[40:41]
	v_pk_mul_f32 v[42:43], v[246:247], v[42:43]
	v_cvt_pk_bf16_f32 v40, v40, v41
	v_pk_mul_f32 v[44:45], v[26:27], v[26:27]
	v_cvt_pk_bf16_f32 v41, v42, v43
	global_store_dwordx2 v[52:53], v[40:41], off offset:512
	s_nop 0
	v_pk_mul_f32 v[46:47], v[24:25], v[24:25]
	s_nop 0
	v_pk_mul_f32 v[36:37], v[248:249], v[36:37]
	v_pk_mul_f32 v[38:39], v[250:251], v[38:39]
	v_cvt_pk_bf16_f32 v36, v36, v37
	v_pk_mul_f32 v[40:41], v[30:31], v[30:31]
	v_cvt_pk_bf16_f32 v37, v38, v39
	global_store_dwordx2 v[52:53], v[36:37], off offset:1024
	s_nop 0
	v_pk_mul_f32 v[42:43], v[28:29], v[28:29]
	s_nop 0
	v_pk_mul_f32 v[32:33], v[32:33], v[252:253]
	v_pk_mul_f32 v[34:35], v[34:35], v[254:255]
	v_cvt_pk_bf16_f32 v32, v32, v33
	v_pk_mov_b32 v[68:69], v[42:43], v[40:41] op_sel:[1,0]
	v_cvt_pk_bf16_f32 v33, v34, v35
	global_store_dwordx2 v[52:53], v[32:33], off offset:1536
	s_nop 0
	v_mov_b32_e32 v43, v41
	v_pk_mov_b32 v[40:41], v[46:47], v[44:45] op_sel:[1,0]
	v_mov_b32_e32 v47, v45
	v_pk_fma_f32 v[44:45], v[20:21], v[20:21], v[48:49] op_sel_hi:[1,1,0]
	v_pk_fma_f32 v[48:49], v[22:23], v[22:23], v[50:51] op_sel_hi:[1,1,0]
	v_pk_mov_b32 v[50:51], v[58:59], v[56:57] op_sel:[1,0]
	v_mov_b32_e32 v59, v57
	v_pk_mov_b32 v[56:57], v[62:63], v[60:61] op_sel:[1,0]
	v_mov_b32_e32 v63, v61
	v_pk_add_f32 v[42:43], v[68:69], v[42:43]
	v_pk_add_f32 v[36:37], v[40:41], v[46:47]
	v_pk_add_f32 v[38:39], v[50:51], v[58:59]
	v_pk_add_f32 v[40:41], v[56:57], v[62:63]
	v_pk_fma_f32 v[60:61], v[4:5], v[4:5], v[64:65] op_sel_hi:[1,1,0]
	v_pk_fma_f32 v[64:65], v[6:7], v[6:7], v[66:67] op_sel_hi:[1,1,0]
	v_pk_add_f32 v[42:43], v[42:43], v[42:43] op_sel_hi:[0,1]
	v_pk_add_f32 v[36:37], v[36:37], v[36:37] op_sel_hi:[0,1]
	v_pk_add_f32 v[38:39], v[38:39], v[38:39] op_sel_hi:[0,1]
	v_pk_add_f32 v[40:41], v[40:41], v[40:41] op_sel_hi:[0,1]
	v_mul_f32_e32 v44, v16, v16
	v_mul_f32_e32 v48, v17, v17
	v_mul_f32_e32 v60, v0, v0
	v_mul_f32_e32 v64, v1, v1
	v_mul_f32_e32 v42, v18, v18
	v_mul_f32_e32 v36, v19, v19
	v_mul_f32_e32 v38, v2, v2
	v_mul_f32_e32 v40, v3, v3
	v_pk_add_f32 v[44:45], v[44:45], v[48:49]
	v_pk_add_f32 v[46:47], v[60:61], v[64:65]
	v_pk_add_f32 v[36:37], v[42:43], v[36:37]
	v_pk_add_f32 v[38:39], v[38:39], v[40:41]
	v_pk_add_f32 v[36:37], v[44:45], v[36:37]
	v_pk_add_f32 v[38:39], v[46:47], v[38:39]
	v_mov_b32_e32 v41, v36
	v_mov_b32_e32 v40, v38
	v_mov_b32_e32 v36, v39
	v_pk_add_f32 v[36:37], v[40:41], v[36:37]
	ds_bpermute_b32 v39, v97, v37
	ds_bpermute_b32 v38, v97, v36
	s_waitcnt lgkmcnt(0)
; __device__ __forceinline__ unsigned pk2(float lo, float hi) { unsigned r; asm("v_cvt_pk_bf16_f32 %0, %1, %2" : "=v"(r) : "v"(lo), "v"(hi)); return r; }
; template <int RB, int XB>
; __device__ __forceinline__ void row_op2(const RowPtrs (&r)[NR], bool has_src, const float* gpost, const float* gnext, int lane) {
;     ...
;         for (int o = 1; o < 64; o <<= 1) {
; #pragma unroll
;             for (int k = 0; k < NR; ++k) ss[k] += __shfl_xor(ss[k], o); }
; #pragma unroll
;         for (int k = 0; k < NR; ++k) { const float rs = rsqrtf(ss[k] * (1.f / D) + EPS);
; #pragma unroll
;             for (int j = 0; j < 4; ++j) { const f32x4 g = ((const f32x4*)gnext)[lane + 64 * j]; const f32x4 h = x[k][j] * rs * g;
;                 u32x2 w; w.x = pk2(h.x, h.y); w.y = pk2(h.z, h.w); ((u32x2*)r[k].hout)[lane + 64 * j] = w; } }
	v_pk_add_f32 v[36:37], v[36:37], v[38:39]
	ds_bpermute_b32 v39, v99, v37
	ds_bpermute_b32 v38, v99, v36
	s_waitcnt lgkmcnt(0)
	v_pk_add_f32 v[36:37], v[36:37], v[38:39]
	ds_bpermute_b32 v39, v109, v37
	ds_bpermute_b32 v38, v109, v36
	s_waitcnt lgkmcnt(0)
	v_pk_add_f32 v[36:37], v[36:37], v[38:39]
	ds_bpermute_b32 v39, v158, v37
	ds_bpermute_b32 v38, v158, v36
	s_waitcnt lgkmcnt(0)
	v_pk_add_f32 v[36:37], v[36:37], v[38:39]
	ds_bpermute_b32 v39, v159, v37
	ds_bpermute_b32 v38, v159, v36
	s_waitcnt lgkmcnt(0)
	v_pk_add_f32 v[36:37], v[36:37], v[38:39]
	ds_bpermute_b32 v39, v160, v37
	ds_bpermute_b32 v38, v160, v36
	s_waitcnt lgkmcnt(0)
	v_pk_add_f32 v[36:37], v[36:37], v[38:39]
	s_nop 0
	v_pk_fma_f32 v[36:37], v[36:37], s[66:67], v[108:109] op_sel_hi:[1,0,0]
	s_nop 0
	v_mul_f32_e32 v38, 0x4b800000, v37
	v_cmp_gt_f32_e32 vcc, s21, v37
	s_nop 1
	v_cndmask_b32_e32 v37, v37, v38, vcc
	v_rsq_f32_e32 v37, v37
	v_lshl_add_u64 v[38:39], s[68:69], 1, v[106:107]
	v_mul_f32_e32 v40, 0x45800000, v37
	v_cndmask_b32_e32 v40, v37, v40, vcc
	v_pk_mul_f32 v[28:29], v[28:29], v[40:41] op_sel_hi:[1,0]
	v_pk_mul_f32 v[30:31], v[30:31], v[40:41] op_sel_hi:[1,0]
	s_nop 0
	v_pk_mul_f32 v[28:29], v[28:29], v[240:241]
	v_pk_mul_f32 v[30:31], v[30:31], v[242:243]
	v_cvt_pk_bf16_f32 v28, v28, v29
	v_pk_mul_f32 v[24:25], v[24:25], v[40:41] op_sel_hi:[1,0]
	v_cvt_pk_bf16_f32 v29, v30, v31
	global_store_dwordx2 v[38:39], v[28:29], off
	s_nop 0
	v_pk_mul_f32 v[26:27], v[26:27], v[40:41] op_sel_hi:[1,0]
	v_pk_mul_f32 v[20:21], v[20:21], v[40:41] op_sel_hi:[1,0]
	v_pk_mul_f32 v[22:23], v[22:23], v[40:41] op_sel_hi:[1,0]
	v_pk_mul_f32 v[16:17], v[16:17], v[40:41] op_sel_hi:[1,0]
	v_pk_mul_f32 v[18:19], v[18:19], v[40:41] op_sel_hi:[1,0]
	v_cmp_gt_f32_e32 vcc, s21, v36
	s_nop 0
	v_pk_mul_f32 v[24:25], v[24:25], v[244:245]
	v_pk_mul_f32 v[26:27], v[26:27], v[246:247]
	v_cvt_pk_bf16_f32 v24, v24, v25
	s_nop 0
	v_cvt_pk_bf16_f32 v25, v26, v27
	global_store_dwordx2 v[38:39], v[24:25], off offset:512
	s_nop 0
	s_nop 0
	v_pk_mul_f32 v[20:21], v[20:21], v[248:249]
	v_pk_mul_f32 v[22:23], v[22:23], v[250:251]
	v_cvt_pk_bf16_f32 v20, v20, v21
	s_nop 0
	v_cvt_pk_bf16_f32 v21, v22, v23
	global_store_dwordx2 v[38:39], v[20:21], off offset:1024
	s_nop 0
	s_nop 0
	v_pk_mul_f32 v[16:17], v[16:17], v[252:253]
	v_pk_mul_f32 v[18:19], v[18:19], v[254:255]
	v_cvt_pk_bf16_f32 v16, v16, v17
	v_mul_f32_e32 v20, 0x4b800000, v36
	v_cvt_pk_bf16_f32 v17, v18, v19
	global_store_dwordx2 v[38:39], v[16:17], off offset:1536
	s_nop 0
	v_cndmask_b32_e32 v20, v36, v20, vcc
	v_rsq_f32_e32 v22, v20
	v_lshl_add_u64 v[20:21], s[70:71], 1, v[106:107]
	v_mul_f32_e32 v23, 0x45800000, v22
	v_cndmask_b32_e32 v22, v22, v23, vcc
	v_pk_mul_f32 v[12:13], v[12:13], v[22:23] op_sel_hi:[1,0]
	v_pk_mul_f32 v[14:15], v[14:15], v[22:23] op_sel_hi:[1,0]
	v_pk_mul_f32 v[8:9], v[8:9], v[22:23] op_sel_hi:[1,0]
	v_pk_mul_f32 v[10:11], v[10:11], v[22:23] op_sel_hi:[1,0]
	v_pk_mul_f32 v[4:5], v[4:5], v[22:23] op_sel_hi:[1,0]
	v_pk_mul_f32 v[6:7], v[6:7], v[22:23] op_sel_hi:[1,0]
	v_pk_mul_f32 v[0:1], v[0:1], v[22:23] op_sel_hi:[1,0]
	v_pk_mul_f32 v[2:3], v[2:3], v[22:23] op_sel_hi:[1,0]
	s_nop 0
	v_pk_mul_f32 v[12:13], v[12:13], v[240:241]
	v_pk_mul_f32 v[14:15], v[14:15], v[242:243]
	v_cvt_pk_bf16_f32 v12, v12, v13
	s_nop 0
	v_cvt_pk_bf16_f32 v13, v14, v15
	global_store_dwordx2 v[20:21], v[12:13], off
	s_nop 0
	s_nop 0
	v_pk_mul_f32 v[8:9], v[8:9], v[244:245]
	v_pk_mul_f32 v[10:11], v[10:11], v[246:247]
	v_cvt_pk_bf16_f32 v8, v8, v9
	s_nop 0
	v_cvt_pk_bf16_f32 v9, v10, v11
	global_store_dwordx2 v[20:21], v[8:9], off offset:512
	s_nop 0
	s_nop 0
	v_pk_mul_f32 v[4:5], v[4:5], v[248:249]
	v_pk_mul_f32 v[6:7], v[6:7], v[250:251]
	v_cvt_pk_bf16_f32 v4, v4, v5
	s_nop 0
	v_cvt_pk_bf16_f32 v5, v6, v7
	global_store_dwordx2 v[20:21], v[4:5], off offset:1024
	s_nop 0
	s_nop 0
	v_pk_mul_f32 v[0:1], v[0:1], v[252:253]
	v_pk_mul_f32 v[2:3], v[2:3], v[254:255]
	v_cvt_pk_bf16_f32 v0, v0, v1
	s_nop 0
	v_cvt_pk_bf16_f32 v1, v2, v3
	global_store_dwordx2 v[20:21], v[0:1], off offset:1536
	s_branch .LBB0_530

; __device__ __forceinline__ float bf2f(unsigned b) { return __uint_as_float(b << 16); }
; __device__ __forceinline__ unsigned pk2(float lo, float hi) { unsigned r; asm("v_cvt_pk_bf16_f32 %0, %1, %2" : "=v"(r) : "v"(lo), "v"(hi)); return r; }
; __device__ __forceinline__ float gelu_t(float x) { return x * __builtin_amdgcn_rcpf(1.f + __expf(-1.5957691216057308f * (x + 0.044715f * x * x * x))); }
; __device__ __forceinline__ void act_item(int item, u16* UP, const u16* HALO, const float* sconv, const float* wconv, const float* bconv, float* out, int lane) {
;     ...
;         for (int t = 0; t < 16; ++t) {
;             const int row = rb * 64 + tb + t;
;             if (sample && (t & 3) == 0) { const int ns = (row - TP) >> 2; const float* s0 = sconv + (size_t)ns * 2 * FF2;
;                 const f32x2 a = *(const f32x2*)(s0 + j0), b = *(const f32x2*)(s0 + FF + j0), c = *(const f32x2*)(s0 + FF2 + j0), dd = *(const f32x2*)(s0 + FF2 + FF + j0);
;                 g2[0] = a.x; g2[1] = a.y; v2[0] = b.x; v2[1] = b.y; g1[0] = c.x; g1[1] = c.y; v1[0] = dd.x; v1[1] = dd.y; }
;             const float g0[2] = {bf2f(gw[t] & 0xffffu), bf2f(gw[t] >> 16)}, v0[2] = {bf2f(vw[t] & 0xffffu), bf2f(vw[t] >> 16)};
;             float res[2];
; #pragma unroll
;             for (int p = 0; p < 2; ++p) { const float cgv = bg[p] + wgt[0][p] * g2[p] + wgt[1][p] * g1[p] + wgt[2][p] * g0[p];
;                 const float cvv = bv[p] + wvl[0][p] * v2[p] + wvl[1][p] * v1[p] + wvl[2][p] * v0[p]; res[p] = gelu_t(cgv) * cvv;
;                 g2[p] = g1[p]; g1[p] = g0[p]; v2[p] = v1[p]; v1[p] = v0[p]; }
;             *(unsigned*)(UP + (size_t)row * FF2 + j0) = pk2(res[0], res[1]);
.LBB0_783:
	s_and_b64 vcc, exec, s[6:7]
	s_cbranch_vccnz .LBB0_785
	s_add_i32 s68, s81, s83
	s_addk_i32 s68, 0xc004
	s_ashr_i32 s68, s68, 2
	s_mul_hi_i32 s69, s68, 0xb000
	s_mul_i32 s68, s68, 0xb000
	s_add_u32 s68, s22, s68
	s_addc_u32 s69, s23, s69
	v_lshl_add_u64 v[48:49], v[2:3], 2, s[68:69]
	v_add_co_u32_e32 v50, vcc, 0x2000, v48
	s_nop 1
	v_addc_co_u32_e32 v51, vcc, 0, v49, vcc
	v_add_co_u32_e32 v52, vcc, 0x5000, v48
	s_nop 1
	v_addc_co_u32_e32 v53, vcc, 0, v49, vcc
	v_add_co_u32_e32 v54, vcc, 0x8000, v48
	s_nop 1
	v_addc_co_u32_e32 v55, vcc, 0, v49, vcc
	global_load_dwordx2 v[58:59], v[48:49], off
	global_load_dwordx2 v[60:61], v[50:51], off offset:3072
	s_nop 0
	global_load_dwordx2 v[52:53], v[52:53], off offset:2048
	s_nop 0
	global_load_dwordx2 v[56:57], v[54:55], off offset:1024
	s_waitcnt vmcnt(0)
.LBB0_785:
	v_pk_fma_f32 v[48:49], v[4:5], v[58:59], v[16:17]
	v_lshlrev_b32_e32 v62, 16, v86
	v_pk_fma_f32 v[48:49], v[8:9], v[52:53], v[48:49]
	v_and_b32_e32 v63, 0xffff0000, v86
	v_fma_f32 v48, v12, v62, v48
	v_mul_f32_e32 v54, 0x3d372713, v48
	v_fmac_f32_e32 v49, v13, v63
	v_mul_f32_e32 v54, v48, v54
	v_mul_f32_e32 v55, 0x3d372713, v49
	v_fma_f32 v54, v48, v54, v48
	v_mul_f32_e32 v55, v49, v55
	v_mul_f32_e32 v54, 0xbfcc422a, v54
	v_fma_f32 v55, v49, v55, v49
	v_mul_f32_e32 v54, 0x3fb8aa3b, v54
	v_mul_f32_e32 v55, 0xbfcc422a, v55
	v_exp_f32_e32 v54, v54
	v_mul_f32_e32 v55, 0x3fb8aa3b, v55
	v_exp_f32_e32 v55, v55
	v_pk_fma_f32 v[50:51], v[6:7], v[60:61], v[18:19]
	v_add_f32_e32 v54, 1.0, v54
	v_rcp_f32_e32 v54, v54
	v_add_f32_e32 v55, 1.0, v55
	v_rcp_f32_e32 v55, v55
	v_lshlrev_b32_e32 v86, 16, v85
	v_pk_fma_f32 v[50:51], v[10:11], v[56:57], v[50:51]
	v_and_b32_e32 v85, 0xffff0000, v85
	v_fma_f32 v50, v14, v86, v50
	v_mul_f32_e32 v48, v48, v54
	v_mul_f32_e32 v48, v50, v48
	v_fmac_f32_e32 v51, v15, v85
	v_mul_f32_e32 v49, v49, v55
	v_mul_f32_e32 v49, v51, v49
	v_cvt_pk_bf16_f32 v50, v48, v49
	v_add_co_u32_e32 v48, vcc, s74, v46
	v_pk_fma_f32 v[58:59], v[4:5], v[52:53], v[16:17]
	s_nop 0
	v_addc_co_u32_e32 v49, vcc, 0, v47, vcc
	v_lshlrev_b32_e32 v51, 16, v83
	v_fma_f32 v58, v8, v62, v58
	global_store_dword v[48:49], v50, off
	v_and_b32_e32 v49, 0xffff0000, v83
	v_fmac_f32_e32 v59, v9, v63
	v_fmac_f32_e32 v58, v12, v51
	v_mul_f32_e32 v60, 0x3d372713, v58
	v_fmac_f32_e32 v59, v13, v49
	v_mul_f32_e32 v60, v58, v60
	v_mul_f32_e32 v61, 0x3d372713, v59
	v_fma_f32 v60, v58, v60, v58
	v_mul_f32_e32 v61, v59, v61
	v_mul_f32_e32 v60, 0xbfcc422a, v60
	v_fma_f32 v61, v59, v61, v59
	v_mul_f32_e32 v60, 0x3fb8aa3b, v60
	v_mul_f32_e32 v61, 0xbfcc422a, v61
	v_exp_f32_e32 v60, v60
	v_mul_f32_e32 v61, 0x3fb8aa3b, v61
	v_exp_f32_e32 v61, v61
	v_pk_fma_f32 v[56:57], v[6:7], v[56:57], v[18:19]
	v_add_f32_e32 v60, 1.0, v60
	v_rcp_f32_e32 v60, v60
	v_add_f32_e32 v61, 1.0, v61
	v_rcp_f32_e32 v61, v61
	v_lshlrev_b32_e32 v50, 16, v84
	v_fma_f32 v56, v10, v86, v56
	v_fmac_f32_e32 v56, v14, v50
	v_mul_f32_e32 v58, v58, v60
	v_mul_f32_e32 v56, v56, v58
	v_mul_f32_e32 v58, v59, v61
	v_fma_f32 v59, v4, v62, v16
	v_lshlrev_b32_e32 v55, 16, v81
	v_fmac_f32_e32 v59, v8, v51
	v_fmac_f32_e32 v59, v12, v55
	v_mul_f32_e32 v60, 0x3d372713, v59
	v_mul_f32_e32 v60, v59, v60
	v_and_b32_e32 v48, 0xffff0000, v84
	v_fmac_f32_e32 v57, v11, v85
	v_fma_f32 v60, v59, v60, v59
	v_fmac_f32_e32 v57, v40, v48
	v_mul_f32_e32 v60, 0xbfcc422a, v60
	v_mul_f32_e32 v57, v57, v58
	v_cvt_pk_bf16_f32 v58, v56, v57
	v_add_co_u32_e32 v56, vcc, s75, v46
	v_mul_f32_e32 v60, 0x3fb8aa3b, v60
	s_nop 0
	v_addc_co_u32_e32 v57, vcc, 0, v47, vcc
	v_exp_f32_e32 v60, v60
	global_store_dword v[56:57], v58, off offset:3072
	v_fma_f32 v58, v5, v63, v17
	v_and_b32_e32 v53, 0xffff0000, v81
	v_fmac_f32_e32 v58, v9, v49
	v_fmac_f32_e32 v58, v13, v53
	v_add_f32_e32 v57, 1.0, v60
	v_mul_f32_e32 v60, 0x3d372713, v58
	v_mul_f32_e32 v60, v58, v60
	v_fma_f32 v60, v58, v60, v58
	v_mul_f32_e32 v60, 0xbfcc422a, v60
	v_rcp_f32_e32 v57, v57
	v_mul_f32_e32 v60, 0x3fb8aa3b, v60
	v_exp_f32_e32 v60, v60
	v_fma_f32 v56, v6, v86, v18
	v_lshlrev_b32_e32 v54, 16, v82
	v_fmac_f32_e32 v56, v10, v50
	v_fmac_f32_e32 v56, v14, v54
	v_mul_f32_e32 v57, v59, v57
	v_mul_f32_e32 v56, v56, v57
	v_add_f32_e32 v57, 1.0, v60
	v_rcp_f32_e32 v57, v57
	v_fma_f32 v59, v7, v85, v19
	v_and_b32_e32 v52, 0xffff0000, v82
	v_fmac_f32_e32 v59, v42, v48
	v_fmac_f32_e32 v59, v40, v52
	v_mul_f32_e32 v57, v58, v57
	v_mul_f32_e32 v57, v59, v57
	v_cvt_pk_bf16_f32 v58, v56, v57
	v_add_co_u32_e32 v56, vcc, 0x4310000, v46
	v_mov_b32_e32 v59, v52
	s_nop 0
	v_addc_co_u32_e32 v57, vcc, 0, v47, vcc
	global_store_dword v[56:57], v58, off offset:2048
	v_mov_b32_e32 v58, v54
	v_mov_b32_e32 v62, v55
	v_mov_b32_e32 v63, v53
	s_mov_b64 s[68:69], -1
	s_and_b64 vcc, exec, s[0:1]
	v_mov_b64_e32 v[56:57], v[62:63]
	v_mov_b64_e32 v[60:61], v[58:59]
	s_cbranch_vccnz .LBB0_787
	v_mov_b32_e32 v56, v55
	v_mov_b32_e32 v57, v53
	v_mov_b32_e32 v60, v54
	v_mov_b32_e32 v61, v52
	s_mov_b64 s[68:69], 0

; __device__ __forceinline__ float bf2f(unsigned b) { return __uint_as_float(b << 16); }
; __device__ __forceinline__ unsigned pk2(float lo, float hi) { unsigned r; asm("v_cvt_pk_bf16_f32 %0, %1, %2" : "=v"(r) : "v"(lo), "v"(hi)); return r; }
; __device__ __forceinline__ float gelu_t(float x) { return x * __builtin_amdgcn_rcpf(1.f + __expf(-1.5957691216057308f * (x + 0.044715f * x * x * x))); }
; __device__ __forceinline__ void act_item(int item, u16* UP, const u16* HALO, const float* sconv, const float* wconv, const float* bconv, float* out, int lane) {
;     ...
;         for (int t = 0; t < 16; ++t) {
;             const int row = rb * 64 + tb + t;
;             if (sample && (t & 3) == 0) { const int ns = (row - TP) >> 2; const float* s0 = sconv + (size_t)ns * 2 * FF2;
;                 const f32x2 a = *(const f32x2*)(s0 + j0), b = *(const f32x2*)(s0 + FF + j0), c = *(const f32x2*)(s0 + FF2 + j0), dd = *(const f32x2*)(s0 + FF2 + FF + j0);
;                 g2[0] = a.x; g2[1] = a.y; v2[0] = b.x; v2[1] = b.y; g1[0] = c.x; g1[1] = c.y; v1[0] = dd.x; v1[1] = dd.y; }
;             const float g0[2] = {bf2f(gw[t] & 0xffffu), bf2f(gw[t] >> 16)}, v0[2] = {bf2f(vw[t] & 0xffffu), bf2f(vw[t] >> 16)};
;             float res[2];
; #pragma unroll
;             for (int p = 0; p < 2; ++p) { const float cgv = bg[p] + wgt[0][p] * g2[p] + wgt[1][p] * g1[p] + wgt[2][p] * g0[p];
;                 const float cvv = bv[p] + wvl[0][p] * v2[p] + wvl[1][p] * v1[p] + wvl[2][p] * v0[p]; res[p] = gelu_t(cgv) * cvv;
;                 g2[p] = g1[p]; g1[p] = g0[p]; v2[p] = v1[p]; v1[p] = v0[p]; }
;             *(unsigned*)(UP + (size_t)row * FF2 + j0) = pk2(res[0], res[1]);
.LBB0_791:
	s_and_b64 vcc, exec, s[6:7]
	s_cbranch_vccnz .LBB0_793
	s_add_i32 s68, s81, s83
	s_addk_i32 s68, 0xc008
	s_ashr_i32 s68, s68, 2
	s_mul_hi_i32 s69, s68, 0xb000
	s_mul_i32 s68, s68, 0xb000
	s_add_u32 s68, s22, s68
	s_addc_u32 s69, s23, s69
	v_lshl_add_u64 v[48:49], v[2:3], 2, s[68:69]
	v_add_co_u32_e32 v50, vcc, 0x2000, v48
	s_nop 1
	v_addc_co_u32_e32 v51, vcc, 0, v49, vcc
	v_add_co_u32_e32 v52, vcc, 0x5000, v48
	s_nop 1
	v_addc_co_u32_e32 v53, vcc, 0, v49, vcc
	v_add_co_u32_e32 v54, vcc, 0x8000, v48
	s_nop 1
	v_addc_co_u32_e32 v55, vcc, 0, v49, vcc
	global_load_dwordx2 v[56:57], v[48:49], off
	global_load_dwordx2 v[60:61], v[50:51], off offset:3072
	s_nop 0
	global_load_dwordx2 v[50:51], v[52:53], off offset:2048
	global_load_dwordx2 v[58:59], v[54:55], off offset:1024
	s_waitcnt vmcnt(0)
.LBB0_793:
	v_pk_fma_f32 v[48:49], v[4:5], v[56:57], v[16:17]
	v_lshlrev_b32_e32 v54, 16, v78
	v_pk_fma_f32 v[48:49], v[8:9], v[50:51], v[48:49]
	v_and_b32_e32 v55, 0xffff0000, v78
	v_fma_f32 v48, v12, v54, v48
	v_mul_f32_e32 v56, 0x3d372713, v48
	v_fmac_f32_e32 v49, v13, v55
	v_mul_f32_e32 v56, v48, v56
	v_mul_f32_e32 v57, 0x3d372713, v49
	v_fma_f32 v56, v48, v56, v48
	v_mul_f32_e32 v57, v49, v57
	v_mul_f32_e32 v56, 0xbfcc422a, v56
	v_fma_f32 v57, v49, v57, v49
	v_mul_f32_e32 v56, 0x3fb8aa3b, v56
	v_mul_f32_e32 v57, 0xbfcc422a, v57
	v_exp_f32_e32 v56, v56
	v_mul_f32_e32 v57, 0x3fb8aa3b, v57
	v_exp_f32_e32 v57, v57
	v_pk_fma_f32 v[52:53], v[6:7], v[60:61], v[18:19]
	v_add_f32_e32 v56, 1.0, v56
	v_rcp_f32_e32 v56, v56
	v_add_f32_e32 v57, 1.0, v57
	v_rcp_f32_e32 v57, v57
	v_lshlrev_b32_e32 v62, 16, v77
	v_pk_fma_f32 v[52:53], v[10:11], v[58:59], v[52:53]
	v_and_b32_e32 v63, 0xffff0000, v77
	v_fma_f32 v52, v14, v62, v52
	v_mul_f32_e32 v48, v48, v56
	v_mul_f32_e32 v48, v52, v48
	v_fmac_f32_e32 v53, v15, v63
	v_mul_f32_e32 v49, v49, v57
	v_mul_f32_e32 v49, v53, v49
	v_cvt_pk_bf16_f32 v52, v48, v49
	v_add_co_u32_e32 v48, vcc, s76, v46
	v_pk_fma_f32 v[50:51], v[4:5], v[50:51], v[16:17]
	s_nop 0
	v_addc_co_u32_e32 v49, vcc, 0, v47, vcc
	global_store_dword v[48:49], v52, off
	v_and_b32_e32 v49, 0xffff0000, v75
	v_fmac_f32_e32 v51, v9, v55
	v_fmac_f32_e32 v51, v13, v49
	v_pk_fma_f32 v[52:53], v[6:7], v[58:59], v[18:19]
	v_lshlrev_b32_e32 v60, 16, v74
	v_and_b32_e32 v58, 0xffff0000, v74
	v_mul_f32_e32 v74, 0x3d372713, v51
	v_mul_f32_e32 v74, v51, v74
	v_fma_f32 v74, v51, v74, v51
	v_mul_f32_e32 v74, 0xbfcc422a, v74
	v_lshlrev_b32_e32 v57, 16, v75
	v_fma_f32 v50, v8, v54, v50
	v_mul_f32_e32 v74, 0x3fb8aa3b, v74
	v_fmac_f32_e32 v50, v12, v57
	v_exp_f32_e32 v74, v74
	v_lshlrev_b32_e32 v61, 16, v73
	v_and_b32_e32 v59, 0xffff0000, v73
	v_mul_f32_e32 v73, 0x3d372713, v50
	v_mul_f32_e32 v73, v50, v73
	v_fma_f32 v73, v50, v73, v50
	v_mul_f32_e32 v73, 0xbfcc422a, v73
	v_add_f32_e32 v74, 1.0, v74
	v_mul_f32_e32 v73, 0x3fb8aa3b, v73
	v_rcp_f32_e32 v74, v74
	v_exp_f32_e32 v73, v73
	v_and_b32_e32 v48, 0xffff0000, v76
	v_fmac_f32_e32 v53, v11, v63
	v_fmac_f32_e32 v53, v40, v48
	v_mul_f32_e32 v51, v51, v74
	v_add_f32_e32 v73, 1.0, v73
	v_mul_f32_e32 v51, v53, v51
	v_fma_f32 v53, v4, v54, v16
	v_rcp_f32_e32 v73, v73
	v_fmac_f32_e32 v53, v8, v57
	v_fmac_f32_e32 v53, v12, v61
	v_mul_f32_e32 v54, 0x3d372713, v53
	v_lshlrev_b32_e32 v56, 16, v76
	v_fma_f32 v52, v10, v62, v52
	v_mul_f32_e32 v54, v53, v54
	v_fmac_f32_e32 v52, v14, v56
	v_mul_f32_e32 v50, v50, v73
	v_fma_f32 v54, v53, v54, v53
	v_mul_f32_e32 v50, v52, v50
	v_mul_f32_e32 v54, 0xbfcc422a, v54
	v_cvt_pk_bf16_f32 v52, v50, v51
	v_add_co_u32_e32 v50, vcc, s77, v46
	v_mul_f32_e32 v54, 0x3fb8aa3b, v54
	s_nop 0
	v_addc_co_u32_e32 v51, vcc, 0, v47, vcc
	v_exp_f32_e32 v54, v54
	global_store_dword v[50:51], v52, off offset:3072
	v_fma_f32 v52, v5, v55, v17
	v_fmac_f32_e32 v52, v9, v49
	v_fmac_f32_e32 v52, v13, v59
	v_add_f32_e32 v51, 1.0, v54
	v_mul_f32_e32 v54, 0x3d372713, v52
	v_mul_f32_e32 v54, v52, v54
	v_fma_f32 v54, v52, v54, v52
	v_mul_f32_e32 v54, 0xbfcc422a, v54
	v_rcp_f32_e32 v51, v51
	v_mul_f32_e32 v54, 0x3fb8aa3b, v54
	v_exp_f32_e32 v54, v54
	v_fma_f32 v50, v6, v62, v18
	v_fmac_f32_e32 v50, v10, v56
	v_fmac_f32_e32 v50, v14, v60
	v_mul_f32_e32 v51, v53, v51
	v_mul_f32_e32 v50, v50, v51
	v_add_f32_e32 v51, 1.0, v54
	v_rcp_f32_e32 v51, v51
	v_fma_f32 v53, v7, v63, v19
	v_fmac_f32_e32 v53, v42, v48
	v_fmac_f32_e32 v53, v40, v58
	v_mul_f32_e32 v51, v52, v51
	v_mul_f32_e32 v51, v53, v51
	v_cvt_pk_bf16_f32 v52, v50, v51
	v_add_co_u32_e32 v50, vcc, 0x431b000, v46
	v_mov_b32_e32 v62, v61
	s_nop 0
	v_addc_co_u32_e32 v51, vcc, 0, v47, vcc
	global_store_dword v[50:51], v52, off offset:2048
	v_mov_b32_e32 v50, v60
	v_mov_b32_e32 v51, v58
	v_mov_b32_e32 v63, v59
	s_mov_b64 s[68:69], -1
	s_and_b64 vcc, exec, s[0:1]
	v_mov_b64_e32 v[52:53], v[62:63]
	v_mov_b64_e32 v[54:55], v[50:51]
	s_cbranch_vccnz .LBB0_795
	v_mov_b32_e32 v52, v61
	v_mov_b32_e32 v53, v59
	v_mov_b32_e32 v54, v60
	v_mov_b32_e32 v55, v58
	s_mov_b64 s[68:69], 0

; __device__ __forceinline__ float bf2f(unsigned b) { return __uint_as_float(b << 16); }
; __device__ __forceinline__ unsigned pk2(float lo, float hi) { unsigned r; asm("v_cvt_pk_bf16_f32 %0, %1, %2" : "=v"(r) : "v"(lo), "v"(hi)); return r; }
; __device__ __forceinline__ float gelu_t(float x) { return x * __builtin_amdgcn_rcpf(1.f + __expf(-1.5957691216057308f * (x + 0.044715f * x * x * x))); }
; __device__ __forceinline__ void act_item(int item, u16* UP, const u16* HALO, const float* sconv, const float* wconv, const float* bconv, float* out, int lane) {
;     ...
;         for (int t = 0; t < 16; ++t) {
;             const int row = rb * 64 + tb + t;
;             if (sample && (t & 3) == 0) { const int ns = (row - TP) >> 2; const float* s0 = sconv + (size_t)ns * 2 * FF2;
;                 const f32x2 a = *(const f32x2*)(s0 + j0), b = *(const f32x2*)(s0 + FF + j0), c = *(const f32x2*)(s0 + FF2 + j0), dd = *(const f32x2*)(s0 + FF2 + FF + j0);
;                 g2[0] = a.x; g2[1] = a.y; v2[0] = b.x; v2[1] = b.y; g1[0] = c.x; g1[1] = c.y; v1[0] = dd.x; v1[1] = dd.y; }
;             const float g0[2] = {bf2f(gw[t] & 0xffffu), bf2f(gw[t] >> 16)}, v0[2] = {bf2f(vw[t] & 0xffffu), bf2f(vw[t] >> 16)};
;             float res[2];
; #pragma unroll
;             for (int p = 0; p < 2; ++p) { const float cgv = bg[p] + wgt[0][p] * g2[p] + wgt[1][p] * g1[p] + wgt[2][p] * g0[p];
;                 const float cvv = bv[p] + wvl[0][p] * v2[p] + wvl[1][p] * v1[p] + wvl[2][p] * v0[p]; res[p] = gelu_t(cgv) * cvv;
;                 g2[p] = g1[p]; g1[p] = g0[p]; v2[p] = v1[p]; v1[p] = v0[p]; }
;             *(unsigned*)(UP + (size_t)row * FF2 + j0) = pk2(res[0], res[1]);
;             if (!sample) { const int tq = row & 2047; if (tq >= 2046) { float* o = out + O_CONVP + ((size_t)(row >> 11) * 2 + (tq - 2046)) * FF2;
;                     *(f32x2*)(o + j0) = (f32x2){g0[0], g0[1]}; *(f32x2*)(o + FF + j0) = (f32x2){v0[0], v0[1]}; } }
.LBB0_800:
	s_add_i32 s84, s81, s83
	s_add_i32 s6, s84, 0xffffc00c
	s_ashr_i32 s6, s6, 2
	s_mul_hi_i32 s7, s6, 0xb000
	s_mul_i32 s6, s6, 0xb000
	s_add_u32 s6, s22, s6
	s_addc_u32 s7, s23, s7
	v_lshl_add_u64 v[48:49], v[2:3], 2, s[6:7]
	v_add_co_u32_e32 v50, vcc, 0x2000, v48
	s_nop 1
	v_addc_co_u32_e32 v51, vcc, 0, v49, vcc
	v_add_co_u32_e32 v56, vcc, 0x5000, v48
	s_nop 1
	v_addc_co_u32_e32 v57, vcc, 0, v49, vcc
	v_add_co_u32_e32 v58, vcc, 0x8000, v48
	s_nop 1
	v_addc_co_u32_e32 v59, vcc, 0, v49, vcc
	global_load_dwordx2 v[52:53], v[48:49], off
	global_load_dwordx2 v[54:55], v[50:51], off offset:3072
	s_nop 0
	global_load_dwordx2 v[48:49], v[56:57], off offset:2048
	global_load_dwordx2 v[50:51], v[58:59], off offset:1024
	s_waitcnt vmcnt(0)
.LBB0_801:
	v_pk_fma_f32 v[52:53], v[4:5], v[52:53], v[16:17]
	v_lshlrev_b32_e32 v71, 16, v70
	v_pk_fma_f32 v[52:53], v[8:9], v[48:49], v[52:53]
	v_and_b32_e32 v70, 0xffff0000, v70
	v_fma_f32 v52, v12, v71, v52
	v_mul_f32_e32 v56, 0x3d372713, v52
	v_fmac_f32_e32 v53, v13, v70
	v_mul_f32_e32 v56, v52, v56
	v_mul_f32_e32 v57, 0x3d372713, v53
	v_fma_f32 v56, v52, v56, v52
	v_mul_f32_e32 v57, v53, v57
	v_mul_f32_e32 v56, 0xbfcc422a, v56
	v_fma_f32 v57, v53, v57, v53
	v_mul_f32_e32 v56, 0x3fb8aa3b, v56
	v_mul_f32_e32 v57, 0xbfcc422a, v57
	v_exp_f32_e32 v56, v56
	v_mul_f32_e32 v57, 0x3fb8aa3b, v57
	v_exp_f32_e32 v57, v57
	v_pk_fma_f32 v[54:55], v[6:7], v[54:55], v[18:19]
	v_add_f32_e32 v56, 1.0, v56
	v_rcp_f32_e32 v56, v56
	v_add_f32_e32 v57, 1.0, v57
	v_rcp_f32_e32 v57, v57
	v_lshlrev_b32_e32 v72, 16, v69
	v_pk_fma_f32 v[54:55], v[10:11], v[50:51], v[54:55]
	v_and_b32_e32 v69, 0xffff0000, v69
	v_fma_f32 v54, v14, v72, v54
	v_mul_f32_e32 v52, v52, v56
	v_mul_f32_e32 v52, v54, v52
	v_fmac_f32_e32 v55, v15, v69
	v_mul_f32_e32 v53, v53, v57
	v_pk_fma_f32 v[48:49], v[4:5], v[48:49], v[16:17]
	v_mul_f32_e32 v53, v55, v53
	v_cvt_pk_bf16_f32 v54, v52, v53
	v_add_co_u32_e32 v52, vcc, s78, v46
	v_and_b32_e32 v57, 0xffff0000, v66
	v_fmac_f32_e32 v49, v9, v70
	v_addc_co_u32_e32 v53, vcc, 0, v47, vcc
	v_fmac_f32_e32 v49, v13, v57
	global_store_dword v[52:53], v54, off
	v_mul_f32_e32 v53, 0x3d372713, v49
	v_mul_f32_e32 v53, v49, v53
	v_lshlrev_b32_e32 v59, 16, v66
	v_fma_f32 v48, v8, v71, v48
	v_fma_f32 v53, v49, v53, v49
	v_fmac_f32_e32 v48, v12, v59
	v_mul_f32_e32 v53, 0xbfcc422a, v53
	v_mul_f32_e32 v52, 0x3d372713, v48
	v_mul_f32_e32 v53, 0x3fb8aa3b, v53
	v_mul_f32_e32 v52, v48, v52
	v_exp_f32_e32 v53, v53
	v_fma_f32 v52, v48, v52, v48
	v_mul_f32_e32 v52, 0xbfcc422a, v52
	v_mul_f32_e32 v52, 0x3fb8aa3b, v52
	v_exp_f32_e32 v52, v52
	v_add_f32_e32 v53, 1.0, v53
	v_rcp_f32_e32 v53, v53
	v_pk_fma_f32 v[50:51], v[6:7], v[50:51], v[18:19]
	v_and_b32_e32 v56, 0xffff0000, v67
	v_fmac_f32_e32 v51, v11, v69
	v_add_f32_e32 v52, 1.0, v52
	v_rcp_f32_e32 v52, v52
	v_fmac_f32_e32 v51, v40, v56
	v_mul_f32_e32 v49, v49, v53
	v_mul_f32_e32 v49, v51, v49
	v_fma_f32 v51, v4, v71, v16
	v_lshlrev_b32_e32 v63, 16, v64
	v_fmac_f32_e32 v51, v8, v59
	v_fmac_f32_e32 v51, v12, v63
	v_mul_f32_e32 v48, v48, v52
	v_mul_f32_e32 v52, 0x3d372713, v51
	v_lshlrev_b32_e32 v58, 16, v67
	v_fma_f32 v50, v10, v72, v50
	v_mul_f32_e32 v52, v51, v52
	v_fmac_f32_e32 v50, v14, v58
	v_fma_f32 v52, v51, v52, v51
	v_mul_f32_e32 v48, v50, v48
	v_mul_f32_e32 v52, 0xbfcc422a, v52
	v_cvt_pk_bf16_f32 v50, v48, v49
	v_add_co_u32_e32 v48, vcc, s79, v46
	v_mul_f32_e32 v52, 0x3fb8aa3b, v52
	s_nop 0
	v_addc_co_u32_e32 v49, vcc, 0, v47, vcc
	v_exp_f32_e32 v52, v52
	global_store_dword v[48:49], v50, off offset:3072
	v_fma_f32 v50, v5, v70, v17
	v_and_b32_e32 v61, 0xffff0000, v64
	v_fmac_f32_e32 v50, v9, v57
	v_fmac_f32_e32 v50, v13, v61
	v_add_f32_e32 v49, 1.0, v52
	v_mul_f32_e32 v52, 0x3d372713, v50
	v_mul_f32_e32 v52, v50, v52
	v_fma_f32 v52, v50, v52, v50
	v_mul_f32_e32 v52, 0xbfcc422a, v52
	v_rcp_f32_e32 v49, v49
	v_mul_f32_e32 v52, 0x3fb8aa3b, v52
	v_exp_f32_e32 v52, v52
	v_fma_f32 v48, v6, v72, v18
	v_lshlrev_b32_e32 v62, 16, v65
	v_fmac_f32_e32 v48, v10, v58
	v_fmac_f32_e32 v48, v14, v62
	v_mul_f32_e32 v49, v51, v49
	v_mul_f32_e32 v48, v48, v49
	v_add_f32_e32 v49, 1.0, v52
	v_rcp_f32_e32 v49, v49
	v_fma_f32 v51, v7, v69, v19
	v_and_b32_e32 v60, 0xffff0000, v65
	v_fmac_f32_e32 v51, v42, v56
	v_fmac_f32_e32 v51, v40, v60
	v_mul_f32_e32 v49, v50, v49
	v_mul_f32_e32 v49, v51, v49
	v_cvt_pk_bf16_f32 v50, v48, v49
	v_add_co_u32_e32 v48, vcc, 0x4326000, v46
	v_mov_b32_e32 v52, v62
	s_nop 0
	v_addc_co_u32_e32 v49, vcc, 0, v47, vcc
	v_mov_b32_e32 v53, v60
	v_mov_b32_e32 v54, v63
	v_mov_b32_e32 v55, v61
	global_store_dword v[48:49], v50, off offset:2048
	s_mov_b64 s[6:7], -1
	s_and_b64 vcc, exec, s[0:1]
	v_mov_b64_e32 v[48:49], v[54:55]
	v_mov_b64_e32 v[50:51], v[52:53]
	s_cbranch_vccnz .LBB0_807
	s_add_i32 s6, s84, 14
	s_and_b32 s6, s6, 0x7fe
	v_mov_b32_e32 v64, v62
	v_mov_b32_e32 v65, v60
	v_mov_b32_e32 v66, v63
	v_mov_b32_e32 v67, v61
	s_cmpk_eq_i32 s6, 0x7fe
	s_mov_b64 s[6:7], -1
	v_mov_b64_e32 v[48:49], v[66:67]
	v_mov_b64_e32 v[50:51], v[64:65]
	s_cbranch_scc1 .LBB0_804
	v_mov_b32_e32 v48, v63
	v_mov_b32_e32 v49, v61
	v_mov_b32_e32 v50, v62
	v_mov_b32_e32 v51, v60
	s_mov_b64 s[6:7], 0

; __global__ void __launch_bounds__(512, 2) fwd_kernel(Args args) {
;     ...
;     if (IN(8)) {
;         for (int m0 = gw; m0 < T; m0 += NR * NGW) { RowPtrs r[NR];
; #pragma unroll
;             for (int k = 0; k < NR; ++k) { const int m = (m0 + k * NGW < T) ? m0 + k * NGW : m0;
;                 r[k] = RowPtrs{m < TP ? nullptr : FT7 + (size_t)(m - TP) * D, H + (size_t)m * D, X1B + (size_t)m * D, UP + (size_t)m * FF2, H + (size_t)m * D, m >= TP}; }
;             row_op2<1, 1>(r, true, args.in[I_GFFNPOST], args.in[I_GPLEIN], lane); }
.LBB0_984:
	s_cmp_lt_i32 s94, 9
	s_cselect_b64 s[6:7], -1, 0
	s_and_b64 s[22:23], s[6:7], s[0:1]
	s_and_b64 s[0:1], s[22:23], s[30:31]
	s_andn2_b64 vcc, exec, s[0:1]
	s_mul_hi_i32 s19, s34, 0x2c00
	s_mul_i32 s64, s34, 0x2c00
	s_mul_i32 s18, s14, 0x42000
	s_cbranch_vccnz .LBB0_1061
	v_mbcnt_hi_u32_b32 v0, -1, v131
	v_and_b32_e32 v1, 64, v0
	v_add_u32_e32 v1, 64, v1
	v_xor_b32_e32 v2, 1, v0
	v_cmp_lt_i32_e32 vcc, v2, v1
	s_cmp_lg_u64 s[50:51], 0
	s_cselect_b64 s[26:27], -1, 0
	v_cndmask_b32_e32 v2, v0, v2, vcc
	v_lshlrev_b32_e32 v49, 2, v2
	v_xor_b32_e32 v2, 2, v0
	v_cmp_lt_i32_e32 vcc, v2, v1
	s_ashr_i32 s35, s34, 31
	v_readlane_b32 s36, v237, 0
	v_cndmask_b32_e32 v2, v0, v2, vcc
	v_lshlrev_b32_e32 v51, 2, v2
	v_xor_b32_e32 v2, 4, v0
	v_cmp_lt_i32_e32 vcc, v2, v1
	s_add_u32 s28, s92, s64
	v_readlane_b32 s40, v237, 4
	v_cndmask_b32_e32 v2, v0, v2, vcc
	v_lshlrev_b32_e32 v61, 2, v2
	v_xor_b32_e32 v2, 8, v0
	v_cmp_lt_i32_e32 vcc, v2, v1
	v_readlane_b32 s41, v237, 5
	s_addc_u32 s29, s93, s19
	v_cndmask_b32_e32 v2, v0, v2, vcc
	v_lshlrev_b32_e32 v146, 2, v2
	v_xor_b32_e32 v2, 16, v0
	v_cmp_lt_i32_e32 vcc, v2, v1
	s_ashr_i32 s21, s20, 31
	s_lshl_b64 s[0:1], s[34:35], 11
	v_cndmask_b32_e32 v2, v0, v2, vcc
	v_lshlrev_b32_e32 v147, 2, v2
	v_xor_b32_e32 v2, 32, v0
	v_readlane_b32 s37, v237, 1
	v_readlane_b32 s38, v237, 2
	v_readlane_b32 s39, v237, 3
	v_readlane_b32 s42, v237, 6
	v_readlane_b32 s43, v237, 7
	s_mov_b64 s[8:9], s[40:41]
	s_add_u32 s36, s92, s0
	v_mov_b32_e32 v133, 0
	v_cmp_lt_i32_e32 vcc, v2, v1
	s_mov_b64 s[10:11], s[42:43]
	s_addc_u32 s37, s93, s1
	s_lshl_b64 s[38:39], s[20:21], 11
	v_cndmask_b32_e32 v0, v0, v2, vcc
	v_mov_b32_e32 v135, v133
	s_add_u32 s40, s10, s0
	v_or_b32_e32 v48, 0x80, v128
	v_or_b32_e32 v50, 0xc0, v128
	s_mov_b32 s25, 0
	v_lshlrev_b32_e32 v148, 2, v0
	v_lshl_add_u64 v[52:53], s[48:49], 0, v[132:133]
	v_lshl_add_u64 v[54:55], s[50:51], 0, v[132:133]
	v_lshl_add_u64 v[56:57], s[10:11], 0, v[134:135]
	v_lshl_add_u64 v[58:59], s[4:5], 0, v[134:135]
	s_mul_hi_i32 s3, s20, 0x2c00
	s_addc_u32 s41, s11, s1
	s_mov_b32 s21, 0x1c00000
	v_mov_b32_e32 v60, 0x358637bd
	s_mov_b32 s42, 0x3a800000
	s_mov_b32 s33, 0x800000
	s_mov_b32 s35, 0x4300000
	v_mov_b32_e32 v133, 0x2c00
	s_mov_b32 s0, s34
	global_load_dwordx4 v[240:243], v[54:55], off
	global_load_dwordx4 v[244:247], v[54:55], off offset:1024
	global_load_dwordx4 v[248:251], v[54:55], off offset:2048
	global_load_dwordx4 v[252:255], v[54:55], off offset:3072
	s_branch .LBB0_987

; __device__ __forceinline__ float bf2f(unsigned b) { return __uint_as_float(b << 16); }
; template <int RB, int XB>
; __device__ __forceinline__ void row_op2(const RowPtrs (&r)[NR], bool has_src, const float* gpost, const float* gnext, int lane) {
;     ...
;     if (has_src) {
;         u32x2 sb[NR][4];
; #pragma unroll
;         for (int k = 0; k < NR; ++k)
; #pragma unroll
;             for (int j = 0; j < 4; ++j) {
;                 if (r[k].srcf != nullptr) { const float* sf = r[k].srcf; s[k][j] = ((const f32x4*)sf)[lane + 64 * j];
;                     if (r[k].parts4) s[k][j] = (s[k][j] + ((const f32x4*)(sf + (size_t)TS * D))[lane + 64 * j]) + (((const f32x4*)(sf + (size_t)2 * TS * D))[lane + 64 * j] + ((const f32x4*)(sf + (size_t)3 * TS * D))[lane + 64 * j]); }
;                 else sb[k][j] = ((const u32x2*)r[k].srcb)[lane + 64 * j];
;             }
;         float ss[NR];
; #pragma unroll
;         for (int k = 0; k < NR; ++k) { ss[k] = 0.f;
; #pragma unroll
;             for (int j = 0; j < 4; ++j) {
;                 if (r[k].srcf == nullptr) { const u32x2 w = sb[k][j]; s[k][j] = (f32x4){bf2f(w.x & 0xffffu), bf2f(w.x >> 16), bf2f(w.y & 0xffffu), bf2f(w.y >> 16)}; }
;                 ss[k] += (s[k][j].x * s[k][j].x + s[k][j].y * s[k][j].y) + (s[k][j].z * s[k][j].z + s[k][j].w * s[k][j].w); } }
.LBB0_1059:
	s_waitcnt vmcnt(0)
	v_lshlrev_b32_e32 v110, 16, v78
	v_and_b32_e32 v111, 0xffff0000, v78
	v_lshlrev_b32_e32 v112, 16, v79
	v_and_b32_e32 v113, 0xffff0000, v79
	v_lshlrev_b32_e32 v106, 16, v76
	v_and_b32_e32 v107, 0xffff0000, v76
	v_lshlrev_b32_e32 v108, 16, v77
	v_and_b32_e32 v109, 0xffff0000, v77
	v_lshlrev_b32_e32 v76, 16, v70
	v_and_b32_e32 v77, 0xffff0000, v70
	v_lshlrev_b32_e32 v78, 16, v71
	v_and_b32_e32 v79, 0xffff0000, v71
	v_lshlrev_b32_e32 v70, 16, v67
	v_and_b32_e32 v71, 0xffff0000, v67
	v_lshlrev_b32_e32 v67, 16, v88
	v_and_b32_e32 v88, 0xffff0000, v88
	v_lshlrev_b32_e32 v150, 16, v89
	v_and_b32_e32 v89, 0xffff0000, v89
	v_cndmask_b32_e64 v143, v1, v88, s[0:1]
	v_cndmask_b32_e64 v142, v0, v67, s[0:1]
	v_cndmask_b32_e64 v89, v3, v89, s[0:1]
	v_cndmask_b32_e64 v88, v2, v150, s[0:1]
	v_pk_mul_f32 v[0:1], v[88:89], v[88:89]
	v_pk_mul_f32 v[2:3], v[142:143], v[142:143]
	v_lshlrev_b32_e32 v67, 16, v91
	v_pk_mov_b32 v[150:151], v[2:3], v[0:1] op_sel:[1,0]
	v_mov_b32_e32 v3, v1
	v_pk_add_f32 v[0:1], v[150:151], v[2:3]
	v_lshlrev_b32_e32 v2, 16, v90
	v_and_b32_e32 v3, 0xffff0000, v90
	v_and_b32_e32 v150, 0xffff0000, v91
	v_cndmask_b32_e64 v91, v5, v3, s[0:1]
	v_cndmask_b32_e64 v90, v4, v2, s[0:1]
	v_cndmask_b32_e64 v5, v7, v150, s[0:1]
	v_cndmask_b32_e64 v4, v6, v67, s[0:1]
	v_pk_mul_f32 v[2:3], v[4:5], v[4:5]
	v_pk_mul_f32 v[6:7], v[90:91], v[90:91]
	v_lshlrev_b32_e32 v67, 16, v93
	v_pk_mov_b32 v[150:151], v[6:7], v[2:3] op_sel:[1,0]
	v_mov_b32_e32 v7, v3
	v_pk_add_f32 v[2:3], v[150:151], v[6:7]
	v_lshlrev_b32_e32 v6, 16, v92
	v_and_b32_e32 v7, 0xffff0000, v92
	v_and_b32_e32 v150, 0xffff0000, v93
	v_cndmask_b32_e64 v93, v9, v7, s[0:1]
	v_cndmask_b32_e64 v92, v8, v6, s[0:1]
	v_cndmask_b32_e64 v9, v11, v150, s[0:1]
	v_cndmask_b32_e64 v8, v10, v67, s[0:1]
	v_lshlrev_b32_e32 v10, 16, v94
	v_and_b32_e32 v11, 0xffff0000, v94
	v_cndmask_b32_e64 v11, v13, v11, s[0:1]
	v_cndmask_b32_e64 v10, v12, v10, s[0:1]
	v_mul_f32_e32 v12, v10, v10
	v_mul_f32_e32 v13, v11, v11
	v_pk_add_f32 v[0:1], v[0:1], v[0:1] op_sel:[0,1] op_sel_hi:[1,0]
	v_pk_add_f32 v[2:3], v[2:3], v[2:3] op_sel:[0,1] op_sel_hi:[1,0]
	v_lshlrev_b32_e32 v6, 16, v95
	v_and_b32_e32 v7, 0xffff0000, v95
	v_mov_b32_e32 v1, v12
	v_mov_b32_e32 v3, v13
	v_cndmask_b32_e64 v7, v15, v7, s[0:1]
	v_cndmask_b32_e64 v6, v14, v6, s[0:1]
	v_pk_add_f32 v[0:1], v[0:1], v[2:3]
	v_mul_f32_e32 v2, v93, v93
	v_mul_f32_e32 v12, v9, v9
	v_mul_f32_e32 v14, v6, v6
	v_mul_f32_e32 v15, v7, v7
	v_pk_fma_f32 v[2:3], v[92:93], v[92:93], v[2:3] op_sel_hi:[1,1,0]
	v_pk_fma_f32 v[12:13], v[8:9], v[8:9], v[12:13] op_sel_hi:[1,1,0]
	v_mov_b32_e32 v3, v14
	v_mov_b32_e32 v13, v15
	v_pk_add_f32 v[2:3], v[2:3], v[12:13]
	global_load_dwordx4 v[150:153], v[52:53], off offset:1024
	v_pk_add_f32 v[0:1], v[0:1], v[2:3]
	v_lshlrev_b32_e32 v2, 16, v97
	v_add_f32_e32 v67, v0, v1
	v_lshlrev_b32_e32 v0, 16, v96
	v_and_b32_e32 v1, 0xffff0000, v96
	v_and_b32_e32 v3, 0xffff0000, v97
	v_cndmask_b32_e64 v15, v17, v1, s[6:7]
	v_cndmask_b32_e64 v14, v16, v0, s[6:7]
	v_cndmask_b32_e64 v17, v19, v3, s[6:7]
	v_cndmask_b32_e64 v16, v18, v2, s[6:7]
	v_pk_mul_f32 v[0:1], v[16:17], v[16:17]
	v_pk_mul_f32 v[2:3], v[14:15], v[14:15]
	global_load_dwordx4 v[154:157], v[52:53], off offset:3072
	v_pk_mov_b32 v[12:13], v[2:3], v[0:1] op_sel:[1,0]
	v_mov_b32_e32 v3, v1
	v_pk_add_f32 v[0:1], v[12:13], v[2:3]
	v_lshlrev_b32_e32 v2, 16, v98
	v_and_b32_e32 v3, 0xffff0000, v98
	v_lshlrev_b32_e32 v12, 16, v99
	v_and_b32_e32 v13, 0xffff0000, v99
	v_cndmask_b32_e64 v19, v21, v3, s[6:7]
	v_cndmask_b32_e64 v18, v20, v2, s[6:7]
	v_cndmask_b32_e64 v21, v23, v13, s[6:7]
	v_cndmask_b32_e64 v20, v22, v12, s[6:7]
	v_pk_mul_f32 v[2:3], v[20:21], v[20:21]
	v_pk_mul_f32 v[12:13], v[18:19], v[18:19]
	v_pk_add_f32 v[0:1], v[0:1], v[0:1] op_sel:[0,1] op_sel_hi:[1,0]
	v_pk_mov_b32 v[22:23], v[12:13], v[2:3] op_sel:[1,0]
	v_mov_b32_e32 v13, v3
	v_pk_add_f32 v[2:3], v[22:23], v[12:13]
	v_lshlrev_b32_e32 v22, 16, v101
	v_and_b32_e32 v23, 0xffff0000, v101
	v_cndmask_b32_e64 v97, v27, v23, s[6:7]
	v_cndmask_b32_e64 v96, v26, v22, s[6:7]
	v_lshlrev_b32_e32 v22, 16, v102
	v_and_b32_e32 v23, 0xffff0000, v102
	v_cndmask_b32_e64 v27, v29, v23, s[6:7]
	v_cndmask_b32_e64 v26, v28, v22, s[6:7]
	v_lshlrev_b32_e32 v12, 16, v100
	v_and_b32_e32 v13, 0xffff0000, v100
	v_mul_f32_e32 v22, v26, v26
	v_mul_f32_e32 v23, v27, v27
	v_pk_add_f32 v[2:3], v[2:3], v[2:3] op_sel:[0,1] op_sel_hi:[1,0]
	v_cndmask_b32_e64 v95, v25, v13, s[6:7]
	v_cndmask_b32_e64 v94, v24, v12, s[6:7]
	v_lshlrev_b32_e32 v12, 16, v103
	v_and_b32_e32 v13, 0xffff0000, v103
	v_mov_b32_e32 v1, v22
	v_mov_b32_e32 v3, v23
	v_cndmask_b32_e64 v13, v31, v13, s[6:7]
	v_cndmask_b32_e64 v12, v30, v12, s[6:7]
	v_pk_add_f32 v[0:1], v[0:1], v[2:3]
	v_mul_f32_e32 v2, v95, v95
	v_mul_f32_e32 v22, v97, v97
	v_mul_f32_e32 v24, v12, v12
	v_mul_f32_e32 v25, v13, v13
	v_pk_fma_f32 v[2:3], v[94:95], v[94:95], v[2:3] op_sel_hi:[1,1,0]
	v_pk_fma_f32 v[22:23], v[96:97], v[96:97], v[22:23] op_sel_hi:[1,1,0]
	v_mov_b32_e32 v3, v24
	v_mov_b32_e32 v23, v25
	v_pk_add_f32 v[2:3], v[2:3], v[22:23]
	v_lshlrev_b32_e32 v120, 16, v83
	v_pk_add_f32 v[22:23], v[0:1], v[2:3]
	v_lshlrev_b32_e32 v0, 16, v104
	v_and_b32_e32 v1, 0xffff0000, v104
	v_lshlrev_b32_e32 v2, 16, v105
	v_and_b32_e32 v3, 0xffff0000, v105
	v_cndmask_b32_e64 v99, v33, v1, s[8:9]
	v_cndmask_b32_e64 v98, v32, v0, s[8:9]
	v_cndmask_b32_e64 v101, v35, v3, s[8:9]
	v_cndmask_b32_e64 v100, v34, v2, s[8:9]
	v_pk_mul_f32 v[0:1], v[100:101], v[100:101]
	v_pk_mul_f32 v[2:3], v[98:99], v[98:99]
	v_and_b32_e32 v121, 0xffff0000, v83
	v_pk_mov_b32 v[24:25], v[2:3], v[0:1] op_sel:[1,0]
	v_mov_b32_e32 v3, v1
	v_pk_add_f32 v[24:25], v[24:25], v[2:3]
	v_lshlrev_b32_e32 v0, 16, v140
	v_and_b32_e32 v1, 0xffff0000, v140
	v_lshlrev_b32_e32 v2, 16, v141
	v_and_b32_e32 v3, 0xffff0000, v141
	v_cndmask_b32_e64 v103, v41, v1, s[8:9]
	v_cndmask_b32_e64 v102, v40, v0, s[8:9]
	v_cndmask_b32_e64 v105, v43, v3, s[8:9]
	v_cndmask_b32_e64 v104, v42, v2, s[8:9]
	v_pk_mul_f32 v[28:29], v[104:105], v[104:105]
	v_pk_mul_f32 v[30:31], v[102:103], v[102:103]
	global_load_dwordx4 v[0:3], v[52:53], off
	v_pk_mov_b32 v[32:33], v[30:31], v[28:29] op_sel:[1,0]
	v_mov_b32_e32 v31, v29
	v_pk_add_f32 v[28:29], v[32:33], v[30:31]
	v_lshlrev_b32_e32 v30, 16, v138
	v_and_b32_e32 v31, 0xffff0000, v138
	v_lshlrev_b32_e32 v32, 16, v139
	v_and_b32_e32 v33, 0xffff0000, v139
	global_load_dwordx4 v[138:141], v[52:53], off offset:2048
	v_cndmask_b32_e64 v160, v38, v32, s[8:9]
	v_lshlrev_b32_e32 v32, 16, v145
	v_cndmask_b32_e64 v159, v37, v31, s[8:9]
	v_cndmask_b32_e64 v158, v36, v30, s[8:9]
	v_lshlrev_b32_e32 v30, 16, v144
	v_and_b32_e32 v31, 0xffff0000, v144
	v_cndmask_b32_e64 v144, v46, v32, s[8:9]
	ds_bpermute_b32 v32, v49, v67
	v_cndmask_b32_e64 v163, v45, v31, s[8:9]
	v_cndmask_b32_e64 v161, v39, v33, s[8:9]
	v_and_b32_e32 v33, 0xffff0000, v145
	v_cndmask_b32_e64 v162, v44, v30, s[8:9]
	s_waitcnt lgkmcnt(0)
; template <int RB, int XB>
; __device__ __forceinline__ void row_op2(const RowPtrs (&r)[NR], bool has_src, const float* gpost, const float* gnext, int lane) {
;     ...
; #pragma unroll
;         for (int o = 1; o < 64; o <<= 1) {
; #pragma unroll
;             for (int k = 0; k < NR; ++k) ss[k] += __shfl_xor(ss[k], o); }
; #pragma unroll
;         for (int k = 0; k < NR; ++k) { const float rs = rsqrtf(ss[k] * (1.f / D) + EPS);
; #pragma unroll
;             for (int j = 0; j < 4; ++j) { const f32x4 g = ((const f32x4*)gpost)[lane + 64 * j]; x[k][j] = x[k][j] + s[k][j] * rs * g; } }
	v_add_f32_e32 v31, v67, v32
	ds_bpermute_b32 v32, v51, v31
	v_cndmask_b32_e64 v145, v47, v33, s[8:9]
	v_mul_f32_e32 v30, v162, v162
	v_mul_f32_e32 v33, v163, v163
	v_pk_add_f32 v[24:25], v[24:25], v[24:25] op_sel:[0,1] op_sel_hi:[1,0]
	s_waitcnt lgkmcnt(0)
	v_add_f32_e32 v31, v31, v32
	ds_bpermute_b32 v32, v61, v31
	v_pk_add_f32 v[28:29], v[28:29], v[28:29] op_sel:[0,1] op_sel_hi:[1,0]
	v_mov_b32_e32 v25, v30
	v_mov_b32_e32 v29, v33
	v_pk_add_f32 v[24:25], v[24:25], v[28:29]
	s_waitcnt lgkmcnt(0)
	v_add_f32_e32 v31, v31, v32
	ds_bpermute_b32 v32, v146, v31
	v_mul_f32_e32 v28, v159, v159
	v_mul_f32_e32 v30, v161, v161
	v_mul_f32_e32 v34, v144, v144
	v_mul_f32_e32 v35, v145, v145
	v_pk_fma_f32 v[28:29], v[158:159], v[158:159], v[28:29] op_sel_hi:[1,1,0]
	s_waitcnt lgkmcnt(0)
	v_add_f32_e32 v32, v31, v32
	v_pk_fma_f32 v[30:31], v[160:161], v[160:161], v[30:31] op_sel_hi:[1,1,0]
	v_mov_b32_e32 v29, v34
	v_mov_b32_e32 v31, v35
	v_pk_add_f32 v[28:29], v[28:29], v[30:31]
	ds_bpermute_b32 v33, v147, v32
	v_pk_add_f32 v[24:25], v[24:25], v[28:29]
	v_mov_b32_e32 v29, v22
	v_mov_b32_e32 v28, v24
	v_mov_b32_e32 v22, v25
	v_pk_add_f32 v[22:23], v[28:29], v[22:23]
	ds_bpermute_b32 v25, v49, v23
	ds_bpermute_b32 v24, v49, v22
	s_waitcnt lgkmcnt(2)
	v_add_f32_e32 v30, v32, v33
	ds_bpermute_b32 v31, v148, v30
	v_lshlrev_b32_e32 v124, 16, v85
	v_and_b32_e32 v125, 0xffff0000, v85
	s_waitcnt lgkmcnt(1)
	v_pk_add_f32 v[22:23], v[22:23], v[24:25]
	ds_bpermute_b32 v25, v51, v23
	ds_bpermute_b32 v24, v51, v22
	s_waitcnt lgkmcnt(2)
	v_add_f32_e32 v28, v30, v31
	v_fmamk_f32 v28, v28, 0x3a800000, v60
	v_mul_f32_e32 v29, 0x4b800000, v28
	v_cmp_gt_f32_e32 vcc, s33, v28
	s_waitcnt lgkmcnt(0)
	v_pk_add_f32 v[22:23], v[22:23], v[24:25]
	ds_bpermute_b32 v25, v61, v23
	ds_bpermute_b32 v24, v61, v22
	v_cndmask_b32_e32 v28, v28, v29, vcc
	v_rsq_f32_e32 v28, v28
	v_lshlrev_b32_e32 v118, 16, v82
	v_and_b32_e32 v119, 0xffff0000, v82
	s_waitcnt lgkmcnt(0)
	v_pk_add_f32 v[22:23], v[22:23], v[24:25]
	ds_bpermute_b32 v25, v146, v23
	ds_bpermute_b32 v24, v146, v22
	v_mul_f32_e32 v29, 0x45800000, v28
	v_cndmask_b32_e32 v28, v28, v29, vcc
	v_pk_mul_f32 v[8:9], v[28:29], v[8:9] op_sel_hi:[0,1]
	v_pk_mul_f32 v[4:5], v[28:29], v[4:5] op_sel_hi:[0,1]
	s_waitcnt lgkmcnt(0)
	v_pk_add_f32 v[22:23], v[22:23], v[24:25]
	ds_bpermute_b32 v25, v147, v23
	ds_bpermute_b32 v24, v147, v22
	s_waitcnt vmcnt(3)
	v_pk_fma_f32 v[40:41], v[152:153], v[4:5], v[124:125]
	v_pk_mul_f32 v[4:5], v[28:29], v[92:93] op_sel_hi:[0,1]
	v_lshlrev_b32_e32 v114, 16, v80
	v_and_b32_e32 v115, 0xffff0000, v80
	s_waitcnt lgkmcnt(0)
	v_pk_add_f32 v[22:23], v[22:23], v[24:25]
	ds_bpermute_b32 v25, v148, v23
	ds_bpermute_b32 v24, v148, v22
	s_waitcnt vmcnt(0)
	v_pk_fma_f32 v[36:37], v[140:141], v[8:9], v[120:121]
	v_pk_fma_f32 v[38:39], v[138:139], v[4:5], v[118:119]
	v_pk_mul_f32 v[4:5], v[28:29], v[10:11] op_sel_hi:[0,1]
	v_pk_fma_f32 v[34:35], v[154:155], v[4:5], v[114:115]
	s_waitcnt lgkmcnt(0)
	v_pk_add_f32 v[8:9], v[22:23], v[24:25]
	v_lshlrev_b32_e32 v136, 16, v87
	v_pk_fma_f32 v[8:9], v[8:9], s[42:43], v[60:61] op_sel_hi:[1,0,0]
	v_and_b32_e32 v137, 0xffff0000, v87
	v_mul_f32_e32 v10, 0x4b800000, v9
	v_cmp_gt_f32_e32 vcc, s33, v9
	v_lshlrev_b32_e32 v116, 16, v81
	v_and_b32_e32 v117, 0xffff0000, v81
	v_cndmask_b32_e32 v9, v9, v10, vcc
	v_rsq_f32_e32 v9, v9
	v_pk_mul_f32 v[32:33], v[28:29], v[88:89] op_sel_hi:[0,1]
	v_pk_mul_f32 v[6:7], v[28:29], v[6:7] op_sel_hi:[0,1]
	v_lshlrev_b32_e32 v126, 16, v86
	v_mul_f32_e32 v4, 0x45800000, v9
	v_cndmask_b32_e32 v4, v9, v4, vcc
	v_and_b32_e32 v127, 0xffff0000, v86
	v_pk_mul_f32 v[30:31], v[28:29], v[142:143] op_sel_hi:[0,1]
	v_pk_fma_f32 v[42:43], v[2:3], v[32:33], v[136:137]
	v_pk_fma_f32 v[32:33], v[156:157], v[6:7], v[116:117]
	v_pk_mul_f32 v[6:7], v[4:5], v[14:15] op_sel_hi:[0,1]
	v_pk_fma_f32 v[46:47], v[0:1], v[30:31], v[126:127]
	v_pk_mul_f32 v[30:31], v[28:29], v[90:91] op_sel_hi:[0,1]
	v_pk_mul_f32 v[10:11], v[4:5], v[16:17] op_sel_hi:[0,1]
	v_pk_fma_f32 v[28:29], v[0:1], v[6:7], v[110:111]
	v_pk_mul_f32 v[6:7], v[4:5], v[18:19] op_sel_hi:[0,1]
	v_lshlrev_b32_e32 v122, 16, v84
	v_and_b32_e32 v123, 0xffff0000, v84
	v_lshlrev_b32_e32 v84, 16, v74
	v_and_b32_e32 v85, 0xffff0000, v74
	v_pk_fma_f32 v[22:23], v[2:3], v[10:11], v[112:113]
	v_pk_mul_f32 v[10:11], v[4:5], v[20:21] op_sel_hi:[0,1]
	v_pk_fma_f32 v[24:25], v[150:151], v[6:7], v[106:107]
	v_pk_mul_f32 v[6:7], v[4:5], v[94:95] op_sel_hi:[0,1]
	v_pk_fma_f32 v[18:19], v[152:153], v[10:11], v[108:109]
	v_pk_mul_f32 v[10:11], v[4:5], v[96:97] op_sel_hi:[0,1]
	v_pk_fma_f32 v[20:21], v[138:139], v[6:7], v[84:85]
	v_pk_mul_f32 v[6:7], v[4:5], v[26:27] op_sel_hi:[0,1]
	v_mul_f32_e32 v5, 0x4b800000, v8
	v_cmp_gt_f32_e32 vcc, s33, v8
	v_lshlrev_b32_e32 v82, 16, v73
	v_and_b32_e32 v83, 0xffff0000, v73
	v_cndmask_b32_e32 v5, v8, v5, vcc
	v_rsq_f32_e32 v8, v5
	v_pk_mul_f32 v[4:5], v[4:5], v[12:13] op_sel_hi:[0,1]
	v_lshlrev_b32_e32 v80, 16, v72
	v_and_b32_e32 v81, 0xffff0000, v72
	v_pk_fma_f32 v[26:27], v[156:157], v[4:5], v[82:83]
	v_mul_f32_e32 v4, 0x45800000, v8
	v_pk_fma_f32 v[44:45], v[150:151], v[30:31], v[122:123]
	v_pk_fma_f32 v[30:31], v[154:155], v[6:7], v[80:81]
	v_cndmask_b32_e32 v6, v8, v4, vcc
	v_pk_mul_f32 v[4:5], v[6:7], v[98:99] op_sel_hi:[0,1]
	v_lshlrev_b32_e32 v72, 16, v68
	v_and_b32_e32 v73, 0xffff0000, v68
	v_pk_fma_f32 v[14:15], v[0:1], v[4:5], v[76:77]
	v_pk_mul_f32 v[0:1], v[6:7], v[102:103] op_sel_hi:[0,1]
	v_lshlrev_b32_e32 v86, 16, v75
	v_and_b32_e32 v87, 0xffff0000, v75
	v_lshlrev_b32_e32 v74, 16, v69
	v_and_b32_e32 v75, 0xffff0000, v69
	v_lshlrev_b32_e32 v68, 16, v66
	v_and_b32_e32 v69, 0xffff0000, v66
; __device__ __forceinline__ unsigned pk2(float lo, float hi) { unsigned r; asm("v_cvt_pk_bf16_f32 %0, %1, %2" : "=v"(r) : "v"(lo), "v"(hi)); return r; }
; template <int RB, int XB>
; __device__ __forceinline__ void row_op2(const RowPtrs (&r)[NR], bool has_src, const float* gpost, const float* gnext, int lane) {
;     ...
;         for (int k = 0; k < NR; ++k) { const float rs = rsqrtf(ss[k] * (1.f / D) + EPS);
; #pragma unroll
;             for (int j = 0; j < 4; ++j) { const f32x4 g = ((const f32x4*)gpost)[lane + 64 * j]; x[k][j] = x[k][j] + s[k][j] * rs * g; } }
;     }
; #pragma unroll
;     for (int k = 0; k < NR; ++k)
;         if (r[k].xout != nullptr) {
; #pragma unroll
;             for (int j = 0; j < 4; ++j) {
;                 if (XB) { u32x2 wv; wv.x = pk2(x[k][j].x, x[k][j].y); wv.y = pk2(x[k][j].z, x[k][j].w); ((u32x2*)r[k].xout)[lane + 64 * j] = wv; }
;                 else ((f32x4*)r[k].xout)[lane + 64 * j] = x[k][j]; }
;         }
;     if (gnext != nullptr) {
;         float ss[NR];
; #pragma unroll
;         for (int k = 0; k < NR; ++k) { ss[k] = 0.f;
; #pragma unroll
;             for (int j = 0; j < 4; ++j) ss[k] += (x[k][j].x * x[k][j].x + x[k][j].y * x[k][j].y) + (x[k][j].z * x[k][j].z + x[k][j].w * x[k][j].w); }
; #pragma unroll
;         for (int o = 1; o < 64; o <<= 1) {
; #pragma unroll
;             for (int k = 0; k < NR; ++k) ss[k] += __shfl_xor(ss[k], o); }
	v_pk_mul_f32 v[8:9], v[6:7], v[100:101] op_sel_hi:[0,1]
	v_pk_fma_f32 v[12:13], v[150:151], v[0:1], v[72:73]
	v_pk_mul_f32 v[0:1], v[6:7], v[158:159] op_sel_hi:[0,1]
	v_lshlrev_b32_e32 v66, 16, v64
	v_and_b32_e32 v67, 0xffff0000, v64
	v_pk_fma_f32 v[16:17], v[140:141], v[10:11], v[86:87]
	v_pk_fma_f32 v[10:11], v[2:3], v[8:9], v[78:79]
	v_pk_mul_f32 v[2:3], v[6:7], v[104:105] op_sel_hi:[0,1]
	v_pk_fma_f32 v[8:9], v[138:139], v[0:1], v[68:69]
	v_pk_mul_f32 v[68:69], v[6:7], v[162:163] op_sel_hi:[0,1]
	v_pk_fma_f32 v[4:5], v[152:153], v[2:3], v[74:75]
	v_pk_mul_f32 v[2:3], v[6:7], v[160:161] op_sel_hi:[0,1]
	v_pk_mul_f32 v[0:1], v[6:7], v[144:145] op_sel_hi:[0,1]
	v_pk_fma_f32 v[6:7], v[154:155], v[68:69], v[66:67]
	v_lshl_add_u64 v[66:67], s[28:29], 0, v[134:135]
	v_lshlrev_b32_e32 v64, 16, v65
	v_and_b32_e32 v65, 0xffff0000, v65
	v_add_co_u32_e32 v66, vcc, s35, v66
	v_pk_fma_f32 v[0:1], v[156:157], v[0:1], v[64:65]
	v_cvt_pk_bf16_f32 v64, v46, v47
	v_cvt_pk_bf16_f32 v65, v42, v43
	s_nop 0
	v_addc_co_u32_e32 v67, vcc, 0, v67, vcc
	global_store_dwordx2 v[66:67], v[64:65], off
	v_cvt_pk_bf16_f32 v64, v44, v45
	v_cvt_pk_bf16_f32 v65, v40, v41
	global_store_dwordx2 v[66:67], v[64:65], off offset:512
	v_cvt_pk_bf16_f32 v64, v38, v39
	v_cvt_pk_bf16_f32 v65, v36, v37
	global_store_dwordx2 v[66:67], v[64:65], off offset:1024
	v_cvt_pk_bf16_f32 v64, v34, v35
	v_cvt_pk_bf16_f32 v65, v32, v33
	global_store_dwordx2 v[66:67], v[64:65], off offset:1536
	v_cvt_pk_bf16_f32 v64, v28, v29
	v_cvt_pk_bf16_f32 v65, v22, v23
	v_mad_i64_i32 v[66:67], s[0:1], s44, v133, v[58:59]
	global_store_dwordx2 v[66:67], v[64:65], off
	v_cvt_pk_bf16_f32 v64, v24, v25
	v_cvt_pk_bf16_f32 v65, v18, v19
	global_store_dwordx2 v[66:67], v[64:65], off offset:512
	v_cvt_pk_bf16_f32 v64, v20, v21
	v_cvt_pk_bf16_f32 v65, v16, v17
	global_store_dwordx2 v[66:67], v[64:65], off offset:1024
	v_cvt_pk_bf16_f32 v64, v30, v31
	v_cvt_pk_bf16_f32 v65, v26, v27
	global_store_dwordx2 v[66:67], v[64:65], off offset:1536
	v_cvt_pk_bf16_f32 v64, v14, v15
	v_cvt_pk_bf16_f32 v65, v10, v11
	v_mad_i64_i32 v[66:67], s[0:1], s46, v133, v[58:59]
	global_store_dwordx2 v[66:67], v[64:65], off
	v_cvt_pk_bf16_f32 v64, v12, v13
	v_cvt_pk_bf16_f32 v65, v4, v5
	v_pk_fma_f32 v[2:3], v[140:141], v[2:3], v[70:71]
	global_store_dwordx2 v[66:67], v[64:65], off offset:512
	v_cvt_pk_bf16_f32 v64, v8, v9
	v_cvt_pk_bf16_f32 v65, v2, v3
	s_andn2_b64 vcc, exec, s[26:27]
	global_store_dwordx2 v[66:67], v[64:65], off offset:1024
	v_cvt_pk_bf16_f32 v64, v6, v7
	v_cvt_pk_bf16_f32 v65, v0, v1
	global_store_dwordx2 v[66:67], v[64:65], off offset:1536
	s_cbranch_vccnz .LBB0_986
	s_nop 0
	v_pk_mul_f32 v[68:69], v[42:43], v[42:43]
	v_pk_mul_f32 v[70:71], v[46:47], v[46:47]
	v_pk_mul_f32 v[72:73], v[40:41], v[40:41]
	v_pk_mul_f32 v[74:75], v[44:45], v[44:45]
	v_pk_mov_b32 v[80:81], v[70:71], v[68:69] op_sel:[1,0]
	v_mov_b32_e32 v71, v69
	v_pk_mov_b32 v[68:69], v[74:75], v[72:73] op_sel:[1,0]
	v_mov_b32_e32 v75, v73
	v_mul_f32_e32 v76, v38, v38
	v_mul_f32_e32 v78, v36, v36
	v_pk_add_f32 v[70:71], v[80:81], v[70:71]
	v_pk_add_f32 v[68:69], v[68:69], v[74:75]
	v_pk_fma_f32 v[72:73], v[38:39], v[38:39], v[76:77] op_sel_hi:[1,1,0]
	v_pk_fma_f32 v[76:77], v[36:37], v[36:37], v[78:79] op_sel_hi:[1,1,0]
	v_pk_add_f32 v[70:71], v[70:71], v[70:71] op_sel_hi:[0,1]
	v_pk_add_f32 v[68:69], v[68:69], v[68:69] op_sel_hi:[0,1]
	v_mul_f32_e32 v72, v34, v34
	v_mul_f32_e32 v76, v35, v35
	v_mul_f32_e32 v70, v32, v32
	v_mul_f32_e32 v68, v33, v33
	v_pk_add_f32 v[72:73], v[72:73], v[76:77]
	v_pk_add_f32 v[68:69], v[70:71], v[68:69]
	v_pk_mul_f32 v[74:75], v[4:5], v[4:5]
	v_pk_add_f32 v[68:69], v[72:73], v[68:69]
	v_pk_mul_f32 v[72:73], v[14:15], v[14:15]
	v_add_f32_e32 v68, v68, v69
	ds_bpermute_b32 v69, v49, v68
	v_pk_mul_f32 v[76:77], v[12:13], v[12:13]
	v_mul_f32_e32 v78, v8, v8
	v_mul_f32_e32 v80, v2, v2
	s_waitcnt lgkmcnt(0)
	v_add_f32_e32 v68, v68, v69
	ds_bpermute_b32 v69, v51, v68
	s_waitcnt lgkmcnt(0)
	v_add_f32_e32 v68, v68, v69
	ds_bpermute_b32 v69, v61, v68
	s_waitcnt lgkmcnt(0)
	v_add_f32_e32 v68, v68, v69
	ds_bpermute_b32 v69, v146, v68
	s_waitcnt lgkmcnt(0)
	v_add_f32_e32 v68, v68, v69
	ds_bpermute_b32 v69, v147, v68
	s_waitcnt lgkmcnt(0)
	v_add_f32_e32 v68, v68, v69
	ds_bpermute_b32 v69, v148, v68
	s_waitcnt lgkmcnt(0)
; __device__ __forceinline__ unsigned pk2(float lo, float hi) { unsigned r; asm("v_cvt_pk_bf16_f32 %0, %1, %2" : "=v"(r) : "v"(lo), "v"(hi)); return r; }
; template <int RB, int XB>
; __device__ __forceinline__ void row_op2(const RowPtrs (&r)[NR], bool has_src, const float* gpost, const float* gnext, int lane) {
;     ...
;         for (int k = 0; k < NR; ++k) { ss[k] = 0.f;
; #pragma unroll
;             for (int j = 0; j < 4; ++j) ss[k] += (x[k][j].x * x[k][j].x + x[k][j].y * x[k][j].y) + (x[k][j].z * x[k][j].z + x[k][j].w * x[k][j].w); }
; #pragma unroll
;         for (int o = 1; o < 64; o <<= 1) {
; #pragma unroll
;             for (int k = 0; k < NR; ++k) ss[k] += __shfl_xor(ss[k], o); }
; #pragma unroll
;         for (int k = 0; k < NR; ++k) { const float rs = rsqrtf(ss[k] * (1.f / D) + EPS);
; #pragma unroll
;             for (int j = 0; j < 4; ++j) { const f32x4 g = ((const f32x4*)gnext)[lane + 64 * j]; const f32x4 h = x[k][j] * rs * g;
;                 u32x2 w; w.x = pk2(h.x, h.y); w.y = pk2(h.z, h.w); ((u32x2*)r[k].hout)[lane + 64 * j] = w; } }
	v_add_f32_e32 v68, v68, v69
	v_fmamk_f32 v68, v68, 0x3a800000, v60
	v_mul_f32_e32 v69, 0x4b800000, v68
	v_cmp_gt_f32_e32 vcc, s33, v68
	s_nop 1
	v_cndmask_b32_e32 v68, v68, v69, vcc
	v_rsq_f32_e32 v70, v68
	v_add_co_u32_e64 v68, s[0:1], s21, v62
	v_mul_f32_e32 v62, 0x45800000, v70
	v_cndmask_b32_e32 v70, v70, v62, vcc
	v_pk_mul_f32 v[46:47], v[46:47], v[70:71] op_sel_hi:[1,0]
	v_addc_co_u32_e64 v69, s[0:1], 0, v63, s[0:1]
	v_pk_mul_f32 v[42:43], v[42:43], v[70:71] op_sel_hi:[1,0]
	v_pk_mul_f32 v[40:41], v[40:41], v[70:71] op_sel_hi:[1,0]
	s_nop 0
	v_pk_mul_f32 v[46:47], v[240:241], v[46:47]
	v_pk_mul_f32 v[42:43], v[242:243], v[42:43]
	v_cvt_pk_bf16_f32 v46, v46, v47
	v_pk_mul_f32 v[38:39], v[38:39], v[70:71] op_sel_hi:[1,0]
	v_cvt_pk_bf16_f32 v47, v42, v43
	global_store_dwordx2 v[68:69], v[46:47], off
	s_nop 0
	v_pk_mul_f32 v[42:43], v[44:45], v[70:71] op_sel_hi:[1,0]
	v_pk_mul_f32 v[36:37], v[36:37], v[70:71] op_sel_hi:[1,0]
	v_pk_mul_f32 v[34:35], v[34:35], v[70:71] op_sel_hi:[1,0]
	v_pk_mul_f32 v[32:33], v[32:33], v[70:71] op_sel_hi:[1,0]
	v_pk_mul_f32 v[44:45], v[18:19], v[18:19]
	v_pk_mul_f32 v[46:47], v[24:25], v[24:25]
	v_pk_mul_f32 v[66:67], v[10:11], v[10:11]
	s_nop 0
	v_pk_mul_f32 v[42:43], v[244:245], v[42:43]
	v_pk_mul_f32 v[40:41], v[246:247], v[40:41]
	v_cvt_pk_bf16_f32 v42, v42, v43
	v_mul_f32_e32 v62, v20, v20
	v_cvt_pk_bf16_f32 v43, v40, v41
	global_store_dwordx2 v[68:69], v[42:43], off offset:512
	s_nop 0
	v_mul_f32_e32 v64, v16, v16
	s_nop 0
	v_pk_mul_f32 v[38:39], v[248:249], v[38:39]
	v_pk_mul_f32 v[36:37], v[250:251], v[36:37]
	v_cvt_pk_bf16_f32 v38, v38, v39
	v_pk_mul_f32 v[40:41], v[22:23], v[22:23]
	v_cvt_pk_bf16_f32 v39, v36, v37
	global_store_dwordx2 v[68:69], v[38:39], off offset:1024
	s_nop 0
	v_pk_mul_f32 v[42:43], v[28:29], v[28:29]
	s_nop 0
	v_pk_mul_f32 v[34:35], v[34:35], v[252:253]
	v_pk_mul_f32 v[32:33], v[32:33], v[254:255]
	v_cvt_pk_bf16_f32 v34, v34, v35
	v_pk_mov_b32 v[82:83], v[42:43], v[40:41] op_sel:[1,0]
	v_cvt_pk_bf16_f32 v35, v32, v33
	global_store_dwordx2 v[68:69], v[34:35], off offset:1536
	s_nop 0
	v_mov_b32_e32 v43, v41
	v_pk_mov_b32 v[40:41], v[46:47], v[44:45] op_sel:[1,0]
	v_mov_b32_e32 v47, v45
	v_pk_fma_f32 v[44:45], v[20:21], v[20:21], v[62:63] op_sel_hi:[1,1,0]
	v_pk_fma_f32 v[62:63], v[16:17], v[16:17], v[64:65] op_sel_hi:[1,1,0]
	v_pk_mov_b32 v[64:65], v[72:73], v[66:67] op_sel:[1,0]
	v_mov_b32_e32 v73, v67
	v_pk_mov_b32 v[66:67], v[76:77], v[74:75] op_sel:[1,0]
	v_mov_b32_e32 v77, v75
	v_pk_add_f32 v[42:43], v[82:83], v[42:43]
	v_pk_add_f32 v[36:37], v[40:41], v[46:47]
	v_pk_add_f32 v[38:39], v[64:65], v[72:73]
	v_pk_add_f32 v[40:41], v[66:67], v[76:77]
	v_pk_fma_f32 v[74:75], v[8:9], v[8:9], v[78:79] op_sel_hi:[1,1,0]
	v_pk_fma_f32 v[78:79], v[2:3], v[2:3], v[80:81] op_sel_hi:[1,1,0]
	v_pk_add_f32 v[42:43], v[42:43], v[42:43] op_sel_hi:[0,1]
	v_pk_add_f32 v[36:37], v[36:37], v[36:37] op_sel_hi:[0,1]
	v_pk_add_f32 v[38:39], v[38:39], v[38:39] op_sel_hi:[0,1]
	v_pk_add_f32 v[40:41], v[40:41], v[40:41] op_sel_hi:[0,1]
	v_mul_f32_e32 v44, v30, v30
	v_mul_f32_e32 v62, v31, v31
	v_mul_f32_e32 v74, v6, v6
	v_mul_f32_e32 v78, v7, v7
	v_mul_f32_e32 v42, v26, v26
	v_mul_f32_e32 v36, v27, v27
	v_mul_f32_e32 v38, v0, v0
	v_mul_f32_e32 v40, v1, v1
	v_pk_add_f32 v[44:45], v[44:45], v[62:63]
	v_pk_add_f32 v[46:47], v[74:75], v[78:79]
	v_pk_add_f32 v[36:37], v[42:43], v[36:37]
	v_pk_add_f32 v[38:39], v[38:39], v[40:41]
	v_pk_add_f32 v[36:37], v[44:45], v[36:37]
	v_pk_add_f32 v[38:39], v[46:47], v[38:39]
	v_mov_b32_e32 v41, v36
	v_mov_b32_e32 v40, v38
	v_mov_b32_e32 v36, v39
	v_pk_add_f32 v[36:37], v[40:41], v[36:37]
	ds_bpermute_b32 v39, v49, v37
	ds_bpermute_b32 v38, v49, v36
	s_waitcnt lgkmcnt(0)
	v_pk_add_f32 v[36:37], v[36:37], v[38:39]
	ds_bpermute_b32 v39, v51, v37
	ds_bpermute_b32 v38, v51, v36
	s_waitcnt lgkmcnt(0)
; __device__ __forceinline__ unsigned pk2(float lo, float hi) { unsigned r; asm("v_cvt_pk_bf16_f32 %0, %1, %2" : "=v"(r) : "v"(lo), "v"(hi)); return r; }
; template <int RB, int XB>
; __device__ __forceinline__ void row_op2(const RowPtrs (&r)[NR], bool has_src, const float* gpost, const float* gnext, int lane) {
;     ...
;         for (int o = 1; o < 64; o <<= 1) {
; #pragma unroll
;             for (int k = 0; k < NR; ++k) ss[k] += __shfl_xor(ss[k], o); }
; #pragma unroll
;         for (int k = 0; k < NR; ++k) { const float rs = rsqrtf(ss[k] * (1.f / D) + EPS);
; #pragma unroll
;             for (int j = 0; j < 4; ++j) { const f32x4 g = ((const f32x4*)gnext)[lane + 64 * j]; const f32x4 h = x[k][j] * rs * g;
;                 u32x2 w; w.x = pk2(h.x, h.y); w.y = pk2(h.z, h.w); ((u32x2*)r[k].hout)[lane + 64 * j] = w; } }
	v_pk_add_f32 v[36:37], v[36:37], v[38:39]
	ds_bpermute_b32 v39, v61, v37
	ds_bpermute_b32 v38, v61, v36
	s_waitcnt lgkmcnt(0)
	v_pk_add_f32 v[36:37], v[36:37], v[38:39]
	ds_bpermute_b32 v39, v146, v37
	ds_bpermute_b32 v38, v146, v36
	s_waitcnt lgkmcnt(0)
	v_pk_add_f32 v[36:37], v[36:37], v[38:39]
	ds_bpermute_b32 v39, v147, v37
	ds_bpermute_b32 v38, v147, v36
	s_waitcnt lgkmcnt(0)
	v_pk_add_f32 v[36:37], v[36:37], v[38:39]
	ds_bpermute_b32 v39, v148, v37
	ds_bpermute_b32 v38, v148, v36
	s_waitcnt lgkmcnt(0)
	v_pk_add_f32 v[36:37], v[36:37], v[38:39]
	s_nop 0
	v_pk_fma_f32 v[36:37], v[36:37], s[42:43], v[60:61] op_sel_hi:[1,0,0]
	s_nop 0
	v_mul_f32_e32 v38, 0x4b800000, v37
	v_cmp_gt_f32_e32 vcc, s33, v37
	s_nop 1
	v_cndmask_b32_e32 v37, v37, v38, vcc
	v_rsq_f32_e32 v37, v37
	s_nop 0
	v_mul_f32_e32 v38, 0x45800000, v37
	v_cndmask_b32_e32 v38, v37, v38, vcc
	v_pk_mul_f32 v[28:29], v[28:29], v[38:39] op_sel_hi:[1,0]
	v_pk_mul_f32 v[22:23], v[22:23], v[38:39] op_sel_hi:[1,0]
	s_nop 0
	v_pk_mul_f32 v[28:29], v[28:29], v[240:241]
	v_pk_mul_f32 v[22:23], v[22:23], v[242:243]
	v_cvt_pk_bf16_f32 v28, v28, v29
	v_pk_mul_f32 v[18:19], v[18:19], v[38:39] op_sel_hi:[1,0]
	v_cvt_pk_bf16_f32 v29, v22, v23
	global_store_dwordx2 v149, v[28:29], s[48:49]
	s_nop 0
	v_pk_mul_f32 v[22:23], v[24:25], v[38:39] op_sel_hi:[1,0]
	v_pk_mul_f32 v[16:17], v[16:17], v[38:39] op_sel_hi:[1,0]
	v_cmp_gt_f32_e32 vcc, s33, v36
	s_nop 0
	v_pk_mul_f32 v[22:23], v[22:23], v[244:245]
	v_pk_mul_f32 v[18:19], v[18:19], v[246:247]
	v_cvt_pk_bf16_f32 v22, v22, v23
	s_nop 0
	v_cvt_pk_bf16_f32 v23, v18, v19
	global_store_dwordx2 v149, v[22:23], s[48:49] offset:512
	s_nop 0
	v_pk_mul_f32 v[18:19], v[20:21], v[38:39] op_sel_hi:[1,0]
	v_pk_mul_f32 v[20:21], v[30:31], v[38:39] op_sel_hi:[1,0]
	s_nop 0
	v_pk_mul_f32 v[18:19], v[18:19], v[248:249]
	v_pk_mul_f32 v[16:17], v[16:17], v[250:251]
	v_cvt_pk_bf16_f32 v18, v18, v19
	v_pk_mul_f32 v[22:23], v[26:27], v[38:39] op_sel_hi:[1,0]
	v_cvt_pk_bf16_f32 v19, v16, v17
	global_store_dwordx2 v149, v[18:19], s[48:49] offset:1024
	s_nop 0
	s_nop 0
	v_pk_mul_f32 v[16:17], v[20:21], v[252:253]
	v_pk_mul_f32 v[18:19], v[22:23], v[254:255]
	v_cvt_pk_bf16_f32 v16, v16, v17
	v_mul_f32_e32 v20, 0x4b800000, v36
	v_cvt_pk_bf16_f32 v17, v18, v19
	global_store_dwordx2 v149, v[16:17], s[48:49] offset:1536
	s_nop 0
	v_cndmask_b32_e32 v20, v36, v20, vcc
	v_rsq_f32_e32 v20, v20
	s_nop 0
	v_mul_f32_e32 v21, 0x45800000, v20
	v_cndmask_b32_e32 v20, v20, v21, vcc
	v_pk_mul_f32 v[14:15], v[14:15], v[20:21] op_sel_hi:[1,0]
	v_pk_mul_f32 v[10:11], v[10:11], v[20:21] op_sel_hi:[1,0]
	v_pk_mul_f32 v[4:5], v[4:5], v[20:21] op_sel_hi:[1,0]
	v_pk_mul_f32 v[2:3], v[2:3], v[20:21] op_sel_hi:[1,0]
	v_pk_mul_f32 v[6:7], v[6:7], v[20:21] op_sel_hi:[1,0]
	v_pk_mul_f32 v[0:1], v[0:1], v[20:21] op_sel_hi:[1,0]
	s_nop 0
	v_pk_mul_f32 v[14:15], v[14:15], v[240:241]
	v_pk_mul_f32 v[10:11], v[10:11], v[242:243]
	v_cvt_pk_bf16_f32 v14, v14, v15
	s_nop 0
	v_cvt_pk_bf16_f32 v15, v10, v11
	global_store_dwordx2 v149, v[14:15], s[50:51]
	s_nop 0
	v_pk_mul_f32 v[10:11], v[12:13], v[20:21] op_sel_hi:[1,0]
	s_nop 0
	v_pk_mul_f32 v[4:5], v[4:5], v[246:247]
	v_pk_mul_f32 v[10:11], v[10:11], v[244:245]
	s_nop 0
	v_cvt_pk_bf16_f32 v10, v10, v11
	v_cvt_pk_bf16_f32 v11, v4, v5
	global_store_dwordx2 v149, v[10:11], s[50:51] offset:512
	s_nop 0
	v_pk_mul_f32 v[4:5], v[8:9], v[20:21] op_sel_hi:[1,0]
	s_nop 0
	v_pk_mul_f32 v[2:3], v[2:3], v[250:251]
	v_pk_mul_f32 v[4:5], v[4:5], v[248:249]
	s_nop 0
	v_cvt_pk_bf16_f32 v4, v4, v5
	v_cvt_pk_bf16_f32 v5, v2, v3
	global_store_dwordx2 v149, v[4:5], s[50:51] offset:1024
	s_nop 0
	s_nop 0
	v_pk_mul_f32 v[2:3], v[6:7], v[252:253]
	v_pk_mul_f32 v[0:1], v[0:1], v[254:255]
	v_cvt_pk_bf16_f32 v2, v2, v3
	s_nop 0
	v_cvt_pk_bf16_f32 v3, v0, v1
	global_store_dwordx2 v149, v[2:3], s[50:51] offset:1536
	s_branch .LBB0_986

; __device__ __forceinline__ float bf2f(unsigned b) { return __uint_as_float(b << 16); }
; __device__ __forceinline__ float sigmoidf_(float x) { return __builtin_amdgcn_rcpf(1.f + __expf(-x)); }
; __device__ __forceinline__ void row_final2(const FinPtrs (&r)[NR], const float* g, int lane) {
;     ...
;             f32x4 pe, gl;
;             { const u32x2 a = ra[k][j]; pe = (f32x4){bf2f(a.x & 0xffffu), bf2f(a.x >> 16), bf2f(a.y & 0xffffu), bf2f(a.y >> 16)}; }
;             if (r[k].gls == nullptr) { const u32x2 b = rb[k][j]; gl = (f32x4){bf2f(b.x & 0xffffu), bf2f(b.x >> 16), bf2f(b.y & 0xffffu), bf2f(b.y >> 16)}; }
;             else { const float* gls = r[k].gls;
;                 gl = (((const f32x4*)gls)[lane + 64 * j] + ((const f32x4*)(gls + (size_t)TS * D))[lane + 64 * j]) + (((const f32x4*)(gls + (size_t)2 * TS * D))[lane + 64 * j] + ((const f32x4*)(gls + (size_t)3 * TS * D))[lane + 64 * j]); }
;             z[k][j] = (f32x4){pe.x * sigmoidf_(gl.x), pe.y * sigmoidf_(gl.y), pe.z * sigmoidf_(gl.z), pe.w * sigmoidf_(gl.w)};
;             ss[k] += (z[k][j].x * z[k][j].x + z[k][j].y * z[k][j].y) + (z[k][j].z * z[k][j].z + z[k][j].w * z[k][j].w);
;         } }
; __global__ void __launch_bounds__(512, 2) fwd_kernel(Args args) {
;     ...
;         for (int m0 = gw; m0 < T; m0 += NR * NGW) { FinPtrs r[NR];
; #pragma unroll
;             for (int k = 0; k < NR; ++k) { const int m = (m0 + k * NGW < T) ? m0 + k * NGW : m0;
;                 r[k] = FinPtrs{UP + (size_t)m * FF2 + FF, UP + (size_t)m * FF2 + FF + D, nullptr, m < TP ? nullptr : GLS + (size_t)(m - TP) * D, UP + (size_t)m * FF2, out + O_Y + (size_t)m * D}; }
;             row_final2(r, args.in[I_GPLEPOST], lane); }
.LBB0_1207:
	s_cmp_lt_i32 s94, 11
	s_cselect_b64 s[2:3], -1, 0
	s_and_b64 s[0:1], s[2:3], s[0:1]
	s_and_b64 s[0:1], s[0:1], s[30:31]
	s_andn2_b64 vcc, exec, s[0:1]
	s_cbranch_vccnz .LBB0_1282
	v_mbcnt_hi_u32_b32 v0, -1, v131
	v_and_b32_e32 v1, 64, v0
	v_add_u32_e32 v1, 64, v1
	v_xor_b32_e32 v2, 1, v0
	v_cmp_lt_i32_e32 vcc, v2, v1
	v_readlane_b32 s8, v237, 0
	v_readlane_b32 s9, v237, 1
	v_cndmask_b32_e32 v2, v0, v2, vcc
	v_lshlrev_b32_e32 v49, 2, v2
	v_xor_b32_e32 v2, 2, v0
	v_cmp_lt_i32_e32 vcc, v2, v1
	v_readlane_b32 s10, v237, 2
	v_readlane_b32 s11, v237, 3
	v_cndmask_b32_e32 v2, v0, v2, vcc
	v_lshlrev_b32_e32 v51, 2, v2
	v_xor_b32_e32 v2, 4, v0
	v_cmp_lt_i32_e32 vcc, v2, v1
	v_readlane_b32 s12, v237, 4
	v_readlane_b32 s13, v237, 5
	v_cndmask_b32_e32 v2, v0, v2, vcc
	v_lshlrev_b32_e32 v61, 2, v2
	v_xor_b32_e32 v2, 8, v0
	v_cmp_lt_i32_e32 vcc, v2, v1
	v_readlane_b32 s14, v237, 6
	v_readlane_b32 s15, v237, 7
	v_cndmask_b32_e32 v2, v0, v2, vcc
	s_mov_b64 s[8:9], s[12:13]
	s_ashr_i32 s35, s34, 31
	v_lshlrev_b32_e32 v112, 2, v2
	v_xor_b32_e32 v2, 16, v0
	s_mov_b64 s[10:11], s[14:15]
	s_lshl_b64 s[0:1], s[34:35], 12
	v_cmp_lt_i32_e32 vcc, v2, v1
	s_add_u32 s0, s10, s0
	s_addc_u32 s1, s11, s1
	v_cndmask_b32_e32 v2, v0, v2, vcc
	s_ashr_i32 s21, s20, 31
	v_mov_b32_e32 v133, 0
	v_lshlrev_b32_e32 v113, 2, v2
	v_xor_b32_e32 v2, 32, v0
	s_lshl_b64 s[6:7], s[20:21], 12
	v_cmp_lt_i32_e32 vcc, v2, v1
	v_lshl_add_u64 v[56:57], s[0:1], 0, v[132:133]
	s_add_u32 s0, s92, s64
	v_cndmask_b32_e32 v0, v0, v2, vcc
	v_mov_b32_e32 v135, v133
	s_addc_u32 s1, s93, s19
	v_lshlrev_b32_e32 v114, 2, v0
	v_lshl_add_u64 v[0:1], s[0:1], 0, v[134:135]
	s_mov_b64 s[0:1], 0x4300000
	v_or_b32_e32 v48, 0x80, v128
	v_or_b32_e32 v50, 0xc0, v128
	s_mov_b32 s3, 0
	v_lshl_add_u64 v[52:53], s[8:9], 0, v[132:133]
	v_lshl_add_u64 v[54:55], s[10:11], 0, v[132:133]
	v_lshl_add_u64 v[58:59], v[0:1], 0, s[0:1]
	s_mul_hi_i32 s19, s20, 0x2c00
	v_mov_b32_e32 v60, 0x358637bd
	s_mov_b32 s8, 0x3a800000
	s_mov_b32 s9, 0x800000
	global_load_dwordx4 v[240:243], v[52:53], off
	global_load_dwordx4 v[244:247], v[52:53], off offset:1024
	global_load_dwordx4 v[248:251], v[52:53], off offset:2048
	global_load_dwordx4 v[252:255], v[52:53], off offset:3072
	s_branch .LBB0_1210
.LBB0_1209:
	v_mul_f32_e32 v20, 0xbfb8aa3b, v20
	v_mul_f32_e32 v21, 0xbfb8aa3b, v21
	v_mul_f32_e32 v22, 0xbfb8aa3b, v22
	v_exp_f32_e32 v20, v20
	v_exp_f32_e32 v21, v21
	v_exp_f32_e32 v22, v22
	v_mul_f32_e32 v23, 0xbfb8aa3b, v23
	v_exp_f32_e32 v23, v23
	v_add_f32_e32 v20, 1.0, v20
	v_add_f32_e32 v21, 1.0, v21
	v_add_f32_e32 v22, 1.0, v22
	v_rcp_f32_e32 v20, v20
	v_rcp_f32_e32 v21, v21
	v_rcp_f32_e32 v116, v22
	v_add_f32_e32 v22, 1.0, v23
	v_rcp_f32_e32 v117, v22
	v_lshlrev_b32_e32 v110, 16, v108
	v_and_b32_e32 v111, 0xffff0000, v108
	v_pk_mul_f32 v[22:23], v[20:21], v[110:111]
	v_lshlrev_b32_e32 v20, 16, v109
	v_and_b32_e32 v21, 0xffff0000, v109
	v_pk_mul_f32 v[108:109], v[116:117], v[20:21]
	v_mov_b32_e32 v110, v23
	v_mov_b32_e32 v111, v109
	v_mov_b32_e32 v20, v22
	v_mov_b32_e32 v21, v108
	v_pk_mul_f32 v[110:111], v[110:111], v[110:111]
	v_mul_f32_e32 v24, 0xbfb8aa3b, v24
	v_pk_fma_f32 v[20:21], v[20:21], v[20:21], v[110:111]
	v_exp_f32_e32 v110, v24
	v_mul_f32_e32 v24, 0xbfb8aa3b, v25
	v_exp_f32_e32 v111, v24
	v_pk_add_f32 v[24:25], v[20:21], v[20:21] op_sel:[0,1] op_sel_hi:[1,0]
	v_add_f32_e32 v20, 1.0, v110
	v_mul_f32_e32 v25, 0xbfb8aa3b, v26
	v_exp_f32_e32 v25, v25
	v_mul_f32_e32 v26, 0xbfb8aa3b, v27
	v_exp_f32_e32 v26, v26
	v_add_f32_e32 v21, 1.0, v111
	v_add_f32_e32 v25, 1.0, v25
	v_rcp_f32_e32 v116, v25
	v_add_f32_e32 v25, 1.0, v26
	v_rcp_f32_e32 v117, v25
	v_mul_f32_e32 v25, 0xbfb8aa3b, v28
	v_rcp_f32_e32 v20, v20
	v_rcp_f32_e32 v21, v21
	v_exp_f32_e32 v25, v25
	v_mul_f32_e32 v28, 0xbfb8aa3b, v29
	v_exp_f32_e32 v29, v28
	v_lshlrev_b32_e32 v110, 16, v106
	v_and_b32_e32 v111, 0xffff0000, v106
	v_pk_mul_f32 v[26:27], v[20:21], v[110:111]
	v_lshlrev_b32_e32 v20, 16, v107
	v_and_b32_e32 v21, 0xffff0000, v107
	v_add_f32_e32 v25, 1.0, v25
	v_pk_mul_f32 v[106:107], v[116:117], v[20:21]
	v_rcp_f32_e32 v28, v25
	v_add_f32_e32 v25, 1.0, v29
	v_mov_b32_e32 v110, v27
	v_mov_b32_e32 v111, v107
	v_rcp_f32_e32 v29, v25
	v_mov_b32_e32 v20, v26
	v_mov_b32_e32 v21, v106
	v_pk_mul_f32 v[110:111], v[110:111], v[110:111]
	v_mul_f32_e32 v25, 0xbfb8aa3b, v30
	v_pk_fma_f32 v[20:21], v[20:21], v[20:21], v[110:111]
	v_exp_f32_e32 v25, v25
	v_pk_add_f32 v[110:111], v[20:21], v[20:21] op_sel:[0,1] op_sel_hi:[1,0]
	v_lshlrev_b32_e32 v20, 16, v104
	v_and_b32_e32 v21, 0xffff0000, v104
	v_pk_mul_f32 v[20:21], v[28:29], v[20:21]
	v_mul_f32_e32 v28, 0xbfb8aa3b, v31
	s_nop 0
	v_exp_f32_e32 v29, v28
	v_add_f32_e32 v25, 1.0, v25
	v_rcp_f32_e32 v30, v25
	v_mul_f32_e32 v28, v21, v21
	v_add_f32_e32 v25, 1.0, v29
	v_rcp_f32_e32 v31, v25
	v_mul_f32_e32 v16, 0xbfb8aa3b, v16
	v_pk_fma_f32 v[120:121], v[20:21], v[20:21], v[28:29] op_sel_hi:[1,1,0]
	v_lshlrev_b32_e32 v28, 16, v105
	v_and_b32_e32 v29, 0xffff0000, v105
	v_exp_f32_e32 v25, v16
	v_mul_f32_e32 v16, 0xbfb8aa3b, v17
	v_pk_mul_f32 v[28:29], v[30:31], v[28:29]
	v_exp_f32_e32 v31, v16
	v_mul_f32_e32 v30, v29, v29
	v_lshlrev_b32_e32 v104, 16, v96
	v_and_b32_e32 v105, 0xffff0000, v96
	v_pk_fma_f32 v[16:17], v[28:29], v[28:29], v[30:31] op_sel_hi:[1,1,0]
	v_lshlrev_b32_e32 v96, 16, v97
	v_add_f32_e32 v17, 1.0, v25
	v_rcp_f32_e32 v30, v17
	v_add_f32_e32 v17, 1.0, v31
	v_rcp_f32_e32 v31, v17
	v_mul_f32_e32 v17, 0xbfb8aa3b, v18
	v_exp_f32_e32 v17, v17
	v_mul_f32_e32 v18, 0xbfb8aa3b, v19
	v_exp_f32_e32 v19, v18
	v_and_b32_e32 v97, 0xffff0000, v97
	v_add_f32_e32 v17, 1.0, v17
	v_rcp_f32_e32 v18, v17
	v_add_f32_e32 v17, 1.0, v19
	v_rcp_f32_e32 v19, v17
	v_pk_mul_f32 v[104:105], v[30:31], v[104:105]
	v_mul_f32_e32 v0, 0xbfb8aa3b, v0
	v_pk_mul_f32 v[30:31], v[104:105], v[104:105]
	v_pk_mul_f32 v[96:97], v[18:19], v[96:97]
	v_mov_b32_e32 v25, v30
	v_pk_mul_f32 v[18:19], v[96:97], v[96:97]
	v_mov_b32_e32 v111, v31
	v_mov_b32_e32 v121, v18
	v_mov_b32_e32 v17, v19
	v_pk_add_f32 v[24:25], v[24:25], v[110:111]
	v_pk_add_f32 v[16:17], v[120:121], v[16:17]
	v_and_b32_e32 v19, 0xffff0000, v89
	v_pk_add_f32 v[16:17], v[24:25], v[16:17]
	v_mul_f32_e32 v1, 0xbfb8aa3b, v1
	v_add_f32_e32 v16, v16, v17
	ds_bpermute_b32 v17, v49, v16
	v_exp_f32_e32 v0, v0
	v_exp_f32_e32 v1, v1
	v_mul_f32_e32 v2, 0xbfb8aa3b, v2
	v_mul_f32_e32 v3, 0xbfb8aa3b, v3
	s_waitcnt lgkmcnt(0)
; __device__ __forceinline__ void row_final2(const FinPtrs (&r)[NR], const float* g, int lane) {
;     ...
;             ss[k] += (z[k][j].x * z[k][j].x + z[k][j].y * z[k][j].y) + (z[k][j].z * z[k][j].z + z[k][j].w * z[k][j].w);
;         } }
; #pragma unroll
;     for (int o = 1; o < 64; o <<= 1) {
; #pragma unroll
;             for (int k = 0; k < NR; ++k) ss[k] += __shfl_xor(ss[k], o); }
; #pragma unroll
;     for (int k = 0; k < NR; ++k) { const float rs = rsqrtf(ss[k] * (1.f / D) + EPS);
; #pragma unroll
;         for (int j = 0; j < 4; ++j) { const f32x4 gv = ((const f32x4*)g)[lane + 64 * j]; ((f32x4*)r[k].yout)[lane + 64 * j] = x[k][j] + z[k][j] * rs * gv; } }
	v_add_f32_e32 v16, v16, v17
	ds_bpermute_b32 v17, v51, v16
	v_exp_f32_e32 v2, v2
	v_exp_f32_e32 v3, v3
	v_add_f32_e32 v0, 1.0, v0
	v_add_f32_e32 v1, 1.0, v1
	s_waitcnt lgkmcnt(0)
	v_add_f32_e32 v16, v16, v17
	ds_bpermute_b32 v17, v61, v16
	v_rcp_f32_e32 v0, v0
	v_rcp_f32_e32 v1, v1
	v_add_f32_e32 v2, 1.0, v2
	v_add_f32_e32 v3, 1.0, v3
	s_waitcnt lgkmcnt(0)
	v_add_f32_e32 v16, v16, v17
	ds_bpermute_b32 v17, v112, v16
	v_rcp_f32_e32 v2, v2
	v_rcp_f32_e32 v3, v3
	s_lshl_b64 s[0:1], s[10:11], 12
	s_add_i32 s34, s96, s33
	s_waitcnt lgkmcnt(0)
	v_add_f32_e32 v16, v16, v17
	ds_bpermute_b32 v17, v113, v16
	v_lshl_add_u64 v[58:59], v[58:59], 0, s[18:19]
	s_waitcnt lgkmcnt(0)
	v_add_f32_e32 v17, v16, v17
	ds_bpermute_b32 v18, v114, v17
	v_lshlrev_b32_e32 v16, 16, v88
	s_waitcnt lgkmcnt(0)
	v_add_f32_e32 v17, v17, v18
	v_fmamk_f32 v17, v17, 0x3a800000, v60
	v_mul_f32_e32 v18, 0x4b800000, v17
	v_cmp_gt_f32_e32 vcc, s9, v17
	s_nop 1
	v_cndmask_b32_e32 v17, v17, v18, vcc
	v_rsq_f32_e32 v24, v17
	v_and_b32_e32 v17, 0xffff0000, v88
	v_lshlrev_b32_e32 v18, 16, v89
	v_mul_f32_e32 v25, 0x45800000, v24
	v_cndmask_b32_e32 v88, v24, v25, vcc
	v_pk_mul_f32 v[22:23], v[22:23], v[88:89] op_sel_hi:[1,0]
	v_pk_mul_f32 v[24:25], v[108:109], v[88:89] op_sel_hi:[1,0]
	s_waitcnt vmcnt(0)
	v_pk_fma_f32 v[16:17], v[240:241], v[22:23], v[16:17]
	v_pk_fma_f32 v[18:19], v[242:243], v[24:25], v[18:19]
	global_store_dwordx4 v[56:57], v[16:19], off
	s_nop 0
	v_pk_mul_f32 v[26:27], v[26:27], v[88:89] op_sel_hi:[1,0]
	v_mul_f32_e32 v16, 0xbfb8aa3b, v36
	v_mul_f32_e32 v17, 0xbfb8aa3b, v37
	v_mul_f32_e32 v19, 0xbfb8aa3b, v38
	v_exp_f32_e32 v16, v16
	v_exp_f32_e32 v17, v17
	v_exp_f32_e32 v22, v19
	v_mul_f32_e32 v19, 0xbfb8aa3b, v39
	v_exp_f32_e32 v23, v19
	v_add_f32_e32 v16, 1.0, v16
	v_add_f32_e32 v17, 1.0, v17
	v_rcp_f32_e32 v16, v16
	v_rcp_f32_e32 v17, v17
	v_add_f32_e32 v22, 1.0, v22
	v_add_f32_e32 v23, 1.0, v23
	v_rcp_f32_e32 v22, v22
	v_rcp_f32_e32 v23, v23
	v_lshlrev_b32_e32 v18, 16, v100
	v_and_b32_e32 v19, 0xffff0000, v100
	v_pk_mul_f32 v[16:17], v[16:17], v[18:19]
	v_lshlrev_b32_e32 v18, 16, v101
	v_and_b32_e32 v19, 0xffff0000, v101
	v_pk_mul_f32 v[18:19], v[22:23], v[18:19]
	v_mov_b32_e32 v24, v17
	v_mov_b32_e32 v25, v19
	v_mov_b32_e32 v22, v16
	v_mov_b32_e32 v23, v18
	v_pk_mul_f32 v[24:25], v[24:25], v[24:25]
	v_mul_f32_e32 v37, 0xbfb8aa3b, v44
	v_pk_fma_f32 v[22:23], v[22:23], v[22:23], v[24:25]
	v_mul_f32_e32 v25, 0xbfb8aa3b, v41
	v_exp_f32_e32 v25, v25
	v_mul_f32_e32 v24, 0xbfb8aa3b, v40
	v_pk_add_f32 v[40:41], v[22:23], v[22:23] op_sel:[0,1] op_sel_hi:[1,0]
	v_exp_f32_e32 v24, v24
	v_add_f32_e32 v23, 1.0, v25
	v_mul_f32_e32 v25, 0xbfb8aa3b, v42
	v_exp_f32_e32 v30, v25
	v_mul_f32_e32 v25, 0xbfb8aa3b, v43
	v_exp_f32_e32 v31, v25
	v_add_f32_e32 v22, 1.0, v24
	v_rcp_f32_e32 v22, v22
	v_rcp_f32_e32 v23, v23
	v_add_f32_e32 v30, 1.0, v30
	v_add_f32_e32 v31, 1.0, v31
	v_rcp_f32_e32 v30, v30
	v_rcp_f32_e32 v31, v31
	v_lshlrev_b32_e32 v24, 16, v102
	v_and_b32_e32 v25, 0xffff0000, v102
	v_pk_mul_f32 v[22:23], v[22:23], v[24:25]
	v_lshlrev_b32_e32 v24, 16, v103
	v_and_b32_e32 v25, 0xffff0000, v103
	v_exp_f32_e32 v38, v37
	v_pk_mul_f32 v[24:25], v[30:31], v[24:25]
	v_mov_b32_e32 v36, v23
	v_mov_b32_e32 v37, v25
	v_mov_b32_e32 v30, v22
	v_mov_b32_e32 v31, v24
	v_pk_mul_f32 v[36:37], v[36:37], v[36:37]
	v_and_b32_e32 v39, 0xffff0000, v83
	v_pk_fma_f32 v[30:31], v[30:31], v[30:31], v[36:37]
	v_add_f32_e32 v36, 1.0, v38
	v_rcp_f32_e32 v42, v36
	v_mul_f32_e32 v36, 0xbfb8aa3b, v45
	v_exp_f32_e32 v41, v36
	v_lshlrev_b32_e32 v36, 16, v82
	v_and_b32_e32 v37, 0xffff0000, v82
	v_lshlrev_b32_e32 v38, 16, v83
	v_pk_mul_f32 v[44:45], v[106:107], v[88:89] op_sel_hi:[1,0]
	v_lshlrev_b32_e32 v82, 16, v90
	v_and_b32_e32 v83, 0xffff0000, v90
	v_pk_mul_f32 v[82:83], v[0:1], v[82:83]
	v_lshlrev_b32_e32 v0, 16, v91
	v_and_b32_e32 v1, 0xffff0000, v91
	v_pk_mul_f32 v[90:91], v[2:3], v[0:1]
	v_mov_b32_e32 v2, v83
	v_mov_b32_e32 v3, v91
	v_mov_b32_e32 v0, v82
	v_mov_b32_e32 v1, v90
	s_nop 0
	v_pk_fma_f32 v[36:37], v[244:245], v[26:27], v[36:37]
	v_pk_fma_f32 v[38:39], v[246:247], v[44:45], v[38:39]
	global_store_dwordx4 v[56:57], v[36:39], off offset:1024
	s_nop 0
	v_pk_mul_f32 v[2:3], v[2:3], v[2:3]
	v_add_f32_e32 v26, 1.0, v41
	v_pk_fma_f32 v[0:1], v[0:1], v[0:1], v[2:3]
	v_mul_f32_e32 v3, 0xbfb8aa3b, v5
	v_exp_f32_e32 v3, v3
	v_mul_f32_e32 v2, 0xbfb8aa3b, v4
	v_pk_add_f32 v[4:5], v[0:1], v[0:1] op_sel:[0,1] op_sel_hi:[1,0]
	v_exp_f32_e32 v2, v2
	v_add_f32_e32 v1, 1.0, v3
	v_mul_f32_e32 v3, 0xbfb8aa3b, v6
	v_exp_f32_e32 v5, v3
	v_mul_f32_e32 v3, 0xbfb8aa3b, v7
	v_exp_f32_e32 v7, v3
	v_pk_add_f32 v[44:45], v[30:31], v[30:31] op_sel:[0,1] op_sel_hi:[1,0]
	v_mul_f32_e32 v30, 0xbfb8aa3b, v46
	v_rcp_f32_e32 v43, v26
	v_exp_f32_e32 v31, v30
	v_mul_f32_e32 v30, 0xbfb8aa3b, v47
	v_exp_f32_e32 v41, v30
	v_add_f32_e32 v0, 1.0, v2
	v_add_f32_e32 v5, 1.0, v5
	v_rcp_f32_e32 v0, v0
	v_rcp_f32_e32 v1, v1
	v_rcp_f32_e32 v6, v5
	v_add_f32_e32 v5, 1.0, v7
	v_lshlrev_b32_e32 v26, 16, v98
	v_and_b32_e32 v27, 0xffff0000, v98
	v_rcp_f32_e32 v7, v5
	v_pk_mul_f32 v[26:27], v[42:43], v[26:27]
	v_add_f32_e32 v31, 1.0, v31
	v_mul_f32_e32 v30, v27, v27
	v_rcp_f32_e32 v42, v31
	v_add_f32_e32 v31, 1.0, v41
	v_lshlrev_b32_e32 v2, 16, v92
	v_and_b32_e32 v3, 0xffff0000, v92
	v_rcp_f32_e32 v43, v31
	v_pk_fma_f32 v[46:47], v[26:27], v[26:27], v[30:31] op_sel_hi:[1,1,0]
	v_lshlrev_b32_e32 v30, 16, v99
	v_and_b32_e32 v31, 0xffff0000, v99
	v_pk_mul_f32 v[98:99], v[0:1], v[2:3]
	v_lshlrev_b32_e32 v0, 16, v93
	v_and_b32_e32 v1, 0xffff0000, v93
	v_pk_mul_f32 v[6:7], v[6:7], v[0:1]
	v_lshlrev_b32_e32 v0, 16, v80
	v_and_b32_e32 v1, 0xffff0000, v80
; __device__ __forceinline__ float bf2f(unsigned b) { return __uint_as_float(b << 16); }
; __device__ __forceinline__ float sigmoidf_(float x) { return __builtin_amdgcn_rcpf(1.f + __expf(-x)); }
; __device__ __forceinline__ void row_final2(const FinPtrs (&r)[NR], const float* g, int lane) {
;     ...
;             f32x4 pe, gl;
;             { const u32x2 a = ra[k][j]; pe = (f32x4){bf2f(a.x & 0xffffu), bf2f(a.x >> 16), bf2f(a.y & 0xffffu), bf2f(a.y >> 16)}; }
;             if (r[k].gls == nullptr) { const u32x2 b = rb[k][j]; gl = (f32x4){bf2f(b.x & 0xffffu), bf2f(b.x >> 16), bf2f(b.y & 0xffffu), bf2f(b.y >> 16)}; }
;             else { const float* gls = r[k].gls;
;                 gl = (((const f32x4*)gls)[lane + 64 * j] + ((const f32x4*)(gls + (size_t)TS * D))[lane + 64 * j]) + (((const f32x4*)(gls + (size_t)2 * TS * D))[lane + 64 * j] + ((const f32x4*)(gls + (size_t)3 * TS * D))[lane + 64 * j]); }
;             z[k][j] = (f32x4){pe.x * sigmoidf_(gl.x), pe.y * sigmoidf_(gl.y), pe.z * sigmoidf_(gl.z), pe.w * sigmoidf_(gl.w)};
;             ss[k] += (z[k][j].x * z[k][j].x + z[k][j].y * z[k][j].y) + (z[k][j].z * z[k][j].z + z[k][j].w * z[k][j].w);
;         } }
; #pragma unroll
;     for (int o = 1; o < 64; o <<= 1) {
; #pragma unroll
;             for (int k = 0; k < NR; ++k) ss[k] += __shfl_xor(ss[k], o); }
; #pragma unroll
;     for (int k = 0; k < NR; ++k) { const float rs = rsqrtf(ss[k] * (1.f / D) + EPS);
; #pragma unroll
;         for (int j = 0; j < 4; ++j) { const f32x4 gv = ((const f32x4*)g)[lane + 64 * j]; ((f32x4*)r[k].yout)[lane + 64 * j] = x[k][j] + z[k][j] * rs * gv; } }
	v_lshlrev_b32_e32 v2, 16, v81
	v_and_b32_e32 v3, 0xffff0000, v81
	v_pk_mul_f32 v[28:29], v[28:29], v[88:89] op_sel_hi:[1,0]
	v_pk_mul_f32 v[20:21], v[20:21], v[88:89] op_sel_hi:[1,0]
	v_mul_f32_e32 v5, 0xbfb8aa3b, v8
	v_exp_f32_e32 v5, v5
	v_mul_f32_e32 v8, 0xbfb8aa3b, v9
	v_mov_b32_e32 v92, v98
	v_mov_b32_e32 v93, v6
	v_add_f32_e32 v5, 1.0, v5
	v_lshlrev_b32_e32 v80, 16, v85
	v_and_b32_e32 v81, 0xffff0000, v85
	v_pk_mul_f32 v[30:31], v[42:43], v[30:31]
	s_nop 0
	v_pk_fma_f32 v[0:1], v[248:249], v[20:21], v[0:1]
	v_pk_fma_f32 v[2:3], v[250:251], v[28:29], v[2:3]
	global_store_dwordx4 v[56:57], v[0:3], off offset:2048
	s_nop 0
	v_exp_f32_e32 v28, v8
	v_mov_b32_e32 v20, v99
	v_mov_b32_e32 v21, v7
	v_pk_mul_f32 v[20:21], v[20:21], v[20:21]
	v_and_b32_e32 v29, 0xffff0000, v86
	v_pk_fma_f32 v[8:9], v[92:93], v[92:93], v[20:21]
	v_rcp_f32_e32 v20, v5
	v_add_f32_e32 v5, 1.0, v28
	v_rcp_f32_e32 v21, v5
	v_pk_add_f32 v[8:9], v[8:9], v[8:9] op_sel:[0,1] op_sel_hi:[1,0]
	v_mul_f32_e32 v5, 0xbfb8aa3b, v10
	v_exp_f32_e32 v5, v5
	v_mul_f32_e32 v9, 0xbfb8aa3b, v11
	v_exp_f32_e32 v9, v9
	v_lshlrev_b32_e32 v28, 16, v86
	v_add_f32_e32 v5, 1.0, v5
	v_pk_mul_f32 v[20:21], v[20:21], v[28:29]
	v_rcp_f32_e32 v28, v5
	v_add_f32_e32 v5, 1.0, v9
	v_rcp_f32_e32 v29, v5
	v_mul_f32_e32 v5, 0xbfb8aa3b, v12
	v_exp_f32_e32 v5, v5
	v_mul_f32_e32 v9, 0xbfb8aa3b, v13
	v_exp_f32_e32 v9, v9
	v_lshlrev_b32_e32 v36, 16, v87
	v_and_b32_e32 v37, 0xffff0000, v87
	v_pk_mul_f32 v[28:29], v[28:29], v[36:37]
	v_add_f32_e32 v5, 1.0, v5
	v_mul_f32_e32 v36, v29, v29
	v_pk_fma_f32 v[12:13], v[28:29], v[28:29], v[36:37] op_sel_hi:[1,1,0]
	v_rcp_f32_e32 v36, v5
	v_add_f32_e32 v5, 1.0, v9
	v_rcp_f32_e32 v37, v5
	v_mul_f32_e32 v5, 0xbfb8aa3b, v14
	v_exp_f32_e32 v5, v5
	v_mul_f32_e32 v9, 0xbfb8aa3b, v15
	v_exp_f32_e32 v9, v9
	v_lshlrev_b32_e32 v38, 16, v84
	v_and_b32_e32 v39, 0xffff0000, v84
	v_add_f32_e32 v5, 1.0, v5
	v_pk_mul_f32 v[14:15], v[36:37], v[38:39]
	v_rcp_f32_e32 v36, v5
	v_add_f32_e32 v5, 1.0, v9
	v_rcp_f32_e32 v37, v5
	v_mul_f32_e32 v10, v21, v21
	v_pk_fma_f32 v[10:11], v[20:21], v[20:21], v[10:11] op_sel_hi:[1,1,0]
	v_pk_mul_f32 v[38:39], v[14:15], v[14:15]
	v_pk_mul_f32 v[36:37], v[36:37], v[80:81]
	v_mov_b32_e32 v5, v38
	v_pk_mul_f32 v[80:81], v[36:37], v[36:37]
	v_mov_b32_e32 v9, v39
	v_mov_b32_e32 v11, v80
	v_mov_b32_e32 v13, v81
	v_pk_add_f32 v[4:5], v[4:5], v[8:9]
	v_pk_add_f32 v[8:9], v[10:11], v[12:13]
	v_mul_f32_e32 v11, 0xbfb8aa3b, v32
	v_exp_f32_e32 v12, v11
	v_mul_f32_e32 v11, 0xbfb8aa3b, v33
	v_pk_add_f32 v[4:5], v[4:5], v[8:9]
	v_lshlrev_b32_e32 v8, 16, v74
	v_and_b32_e32 v9, 0xffff0000, v74
	v_lshlrev_b32_e32 v10, 16, v75
	v_exp_f32_e32 v13, v11
	v_and_b32_e32 v11, 0xffff0000, v75
	v_pk_mul_f32 v[38:39], v[96:97], v[88:89] op_sel_hi:[1,0]
	v_pk_mul_f32 v[74:75], v[104:105], v[88:89] op_sel_hi:[1,0]
	v_mul_f32_e32 v33, 0xbfb8aa3b, v34
	v_add_f32_e32 v12, 1.0, v12
	v_add_f32_e32 v13, 1.0, v13
	v_rcp_f32_e32 v12, v12
	v_rcp_f32_e32 v13, v13
	v_lshlrev_b32_e32 v32, 16, v94
	v_mul_f32_e32 v42, v31, v31
	v_pk_fma_f32 v[42:43], v[30:31], v[30:31], v[42:43] op_sel_hi:[1,1,0]
	s_nop 0
	v_pk_fma_f32 v[0:1], v[252:253], v[74:75], v[8:9]
	v_pk_fma_f32 v[2:3], v[254:255], v[38:39], v[10:11]
	global_store_dwordx4 v[56:57], v[0:3], off offset:3072
	s_nop 0
	v_mul_f32_e32 v9, 0xbfb8aa3b, v35
	v_exp_f32_e32 v8, v33
	v_exp_f32_e32 v9, v9
	v_and_b32_e32 v33, 0xffff0000, v94
	v_pk_mul_f32 v[10:11], v[12:13], v[32:33]
	v_add_f32_e32 v8, 1.0, v8
	v_add_f32_e32 v9, 1.0, v9
	v_rcp_f32_e32 v8, v8
	v_rcp_f32_e32 v9, v9
	v_lshlrev_b32_e32 v12, 16, v95
	v_and_b32_e32 v13, 0xffff0000, v95
	v_lshl_add_u64 v[34:35], v[54:55], 0, s[0:1]
	v_pk_mul_f32 v[8:9], v[8:9], v[12:13]
	v_pk_mul_f32 v[12:13], v[10:11], v[10:11]
	v_pk_mul_f32 v[32:33], v[8:9], v[8:9]
	v_mov_b32_e32 v41, v12
	v_mov_b32_e32 v45, v13
	v_mov_b32_e32 v47, v32
	v_mov_b32_e32 v43, v33
	v_pk_add_f32 v[12:13], v[40:41], v[44:45]
	v_pk_add_f32 v[32:33], v[46:47], v[42:43]
	s_lshl_b64 s[0:1], s[12:13], 12
	v_pk_add_f32 v[12:13], v[12:13], v[32:33]
	v_mov_b32_e32 v33, v4
	v_mov_b32_e32 v32, v12
	v_mov_b32_e32 v4, v13
	v_pk_add_f32 v[4:5], v[32:33], v[4:5]
	ds_bpermute_b32 v13, v49, v5
	ds_bpermute_b32 v12, v49, v4
	v_lshlrev_b32_e32 v32, 16, v62
	v_and_b32_e32 v33, 0xffff0000, v62
	s_cmpk_lt_i32 s34, 0x4200
	v_lshl_add_u64 v[56:57], v[56:57], 0, s[6:7]
	s_waitcnt lgkmcnt(0)
	v_pk_add_f32 v[4:5], v[4:5], v[12:13]
	ds_bpermute_b32 v13, v51, v5
	ds_bpermute_b32 v12, v51, v4
	s_waitcnt lgkmcnt(0)
; __device__ __forceinline__ void row_final2(const FinPtrs (&r)[NR], const float* g, int lane) {
;     ...
; #pragma unroll
;     for (int o = 1; o < 64; o <<= 1) {
; #pragma unroll
;             for (int k = 0; k < NR; ++k) ss[k] += __shfl_xor(ss[k], o); }
; #pragma unroll
;     for (int k = 0; k < NR; ++k) { const float rs = rsqrtf(ss[k] * (1.f / D) + EPS);
; #pragma unroll
;         for (int j = 0; j < 4; ++j) { const f32x4 gv = ((const f32x4*)g)[lane + 64 * j]; ((f32x4*)r[k].yout)[lane + 64 * j] = x[k][j] + z[k][j] * rs * gv; } }
	v_pk_add_f32 v[4:5], v[4:5], v[12:13]
	ds_bpermute_b32 v13, v61, v5
	ds_bpermute_b32 v12, v61, v4
	s_waitcnt lgkmcnt(0)
	v_pk_add_f32 v[4:5], v[4:5], v[12:13]
	ds_bpermute_b32 v13, v112, v5
	ds_bpermute_b32 v12, v112, v4
	s_waitcnt lgkmcnt(0)
	v_pk_add_f32 v[4:5], v[4:5], v[12:13]
	ds_bpermute_b32 v13, v113, v5
	ds_bpermute_b32 v12, v113, v4
	s_waitcnt lgkmcnt(0)
	v_pk_add_f32 v[4:5], v[4:5], v[12:13]
	ds_bpermute_b32 v13, v114, v5
	ds_bpermute_b32 v12, v114, v4
	s_waitcnt lgkmcnt(0)
	v_pk_add_f32 v[4:5], v[4:5], v[12:13]
	s_nop 0
	v_pk_fma_f32 v[4:5], v[4:5], s[8:9], v[60:61] op_sel_hi:[1,0,0]
	v_and_b32_e32 v13, 0xffff0000, v63
	v_mul_f32_e32 v12, 0x4b800000, v5
	v_cmp_gt_f32_e32 vcc, s9, v5
	s_nop 1
	v_cndmask_b32_e32 v5, v5, v12, vcc
	v_rsq_f32_e32 v5, v5
	v_lshlrev_b32_e32 v12, 16, v63
	v_mul_f32_e32 v38, 0x45800000, v5
	v_cndmask_b32_e32 v38, v5, v38, vcc
	v_pk_mul_f32 v[40:41], v[90:91], v[38:39] op_sel_hi:[1,0]
	v_pk_mul_f32 v[42:43], v[82:83], v[38:39] op_sel_hi:[1,0]
	s_nop 0
	v_pk_fma_f32 v[2:3], v[242:243], v[40:41], v[12:13]
	v_pk_fma_f32 v[0:1], v[240:241], v[42:43], v[32:33]
	global_store_dwordx4 v[34:35], v[0:3], off
	s_nop 0
	v_lshlrev_b32_e32 v12, 16, v66
	v_and_b32_e32 v13, 0xffff0000, v66
	v_lshlrev_b32_e32 v32, 16, v67
	v_and_b32_e32 v33, 0xffff0000, v67
	v_pk_mul_f32 v[6:7], v[6:7], v[38:39] op_sel_hi:[1,0]
	v_pk_mul_f32 v[40:41], v[98:99], v[38:39] op_sel_hi:[1,0]
	v_pk_mul_f32 v[28:29], v[28:29], v[38:39] op_sel_hi:[1,0]
	v_pk_mul_f32 v[20:21], v[20:21], v[38:39] op_sel_hi:[1,0]
	v_pk_mul_f32 v[14:15], v[14:15], v[38:39] op_sel_hi:[1,0]
	v_mul_f32_e32 v5, 0x4b800000, v4
	v_cmp_gt_f32_e32 vcc, s9, v4
	s_nop 0
	v_pk_fma_f32 v[0:1], v[40:41], v[244:245], v[12:13]
	v_pk_fma_f32 v[2:3], v[6:7], v[246:247], v[32:33]
	global_store_dwordx4 v[34:35], v[0:3], off offset:1024
	s_nop 0
	v_lshlrev_b32_e32 v6, 16, v68
	v_and_b32_e32 v7, 0xffff0000, v68
	v_lshlrev_b32_e32 v12, 16, v69
	v_and_b32_e32 v13, 0xffff0000, v69
	v_cndmask_b32_e32 v4, v4, v5, vcc
	v_and_b32_e32 v5, 0xffff0000, v71
	s_nop 0
	v_pk_fma_f32 v[0:1], v[20:21], v[248:249], v[6:7]
	v_pk_fma_f32 v[2:3], v[28:29], v[250:251], v[12:13]
	global_store_dwordx4 v[34:35], v[0:3], off offset:2048
	s_nop 0
	v_lshlrev_b32_e32 v6, 16, v64
	v_and_b32_e32 v7, 0xffff0000, v64
	v_lshlrev_b32_e32 v12, 16, v65
	v_and_b32_e32 v13, 0xffff0000, v65
	v_pk_mul_f32 v[20:21], v[36:37], v[38:39] op_sel_hi:[1,0]
	s_nop 0
	v_pk_fma_f32 v[0:1], v[14:15], v[252:253], v[6:7]
	v_pk_fma_f32 v[2:3], v[20:21], v[254:255], v[12:13]
	global_store_dwordx4 v[34:35], v[0:3], off offset:3072
	s_nop 0
	v_rsq_f32_e32 v14, v4
	v_lshlrev_b32_e32 v6, 16, v70
	v_and_b32_e32 v7, 0xffff0000, v70
	v_lshlrev_b32_e32 v4, 16, v71
	v_mul_f32_e32 v15, 0x45800000, v14
	v_cndmask_b32_e32 v14, v14, v15, vcc
	v_pk_mul_f32 v[18:19], v[18:19], v[14:15] op_sel_hi:[1,0]
	v_pk_mul_f32 v[16:17], v[16:17], v[14:15] op_sel_hi:[1,0]
	v_lshl_add_u64 v[12:13], v[54:55], 0, s[0:1]
	v_pk_mul_f32 v[8:9], v[8:9], v[14:15] op_sel_hi:[1,0]
	v_pk_mul_f32 v[10:11], v[10:11], v[14:15] op_sel_hi:[1,0]
	s_nop 0
	v_pk_fma_f32 v[0:1], v[16:17], v[240:241], v[6:7]
	v_pk_fma_f32 v[2:3], v[18:19], v[242:243], v[4:5]
	global_store_dwordx4 v[12:13], v[0:3], off
	s_nop 0
	v_lshlrev_b32_e32 v4, 16, v78
	v_and_b32_e32 v5, 0xffff0000, v78
	v_lshlrev_b32_e32 v6, 16, v79
	v_and_b32_e32 v7, 0xffff0000, v79
	v_pk_mul_f32 v[16:17], v[24:25], v[14:15] op_sel_hi:[1,0]
	v_pk_mul_f32 v[18:19], v[22:23], v[14:15] op_sel_hi:[1,0]
	s_nop 0
	v_pk_fma_f32 v[2:3], v[16:17], v[246:247], v[6:7]
	v_pk_fma_f32 v[0:1], v[18:19], v[244:245], v[4:5]
	global_store_dwordx4 v[12:13], v[0:3], off offset:1024
	s_nop 0
	v_lshlrev_b32_e32 v4, 16, v76
	v_and_b32_e32 v5, 0xffff0000, v76
	v_lshlrev_b32_e32 v6, 16, v77
	v_and_b32_e32 v7, 0xffff0000, v77
	v_pk_mul_f32 v[16:17], v[30:31], v[14:15] op_sel_hi:[1,0]
	v_pk_mul_f32 v[18:19], v[26:27], v[14:15] op_sel_hi:[1,0]
	s_nop 0
	v_pk_fma_f32 v[2:3], v[16:17], v[250:251], v[6:7]
	v_pk_fma_f32 v[0:1], v[18:19], v[248:249], v[4:5]
	global_store_dwordx4 v[12:13], v[0:3], off offset:2048
	s_nop 0
	v_lshlrev_b32_e32 v4, 16, v72
	v_and_b32_e32 v5, 0xffff0000, v72
	v_lshlrev_b32_e32 v6, 16, v73
	v_and_b32_e32 v7, 0xffff0000, v73
	s_nop 0
	v_pk_fma_f32 v[0:1], v[10:11], v[252:253], v[4:5]
	v_pk_fma_f32 v[2:3], v[8:9], v[254:255], v[6:7]
	global_store_dwordx4 v[12:13], v[0:3], off offset:3072
	s_cbranch_scc0 .LBB0_1282

; #define LAS __attribute__((address_space(3)))
; __global__ void __launch_bounds__(512, 2) fwd_kernel(Args args) {
;     extern __shared__ __attribute__((aligned(16))) unsigned char lds_raw[];
;     LAS unsigned char* lds = (LAS unsigned char*)lds_raw;
;     cg::grid_group grid = cg::this_grid();
;     const int tid = threadIdx.x, lane = tid & 63, wave = __builtin_amdgcn_readfirstlane(tid >> 6);
	.amdhsa_kernel _Z10fwd_kernel4Args
		.amdhsa_group_segment_fixed_size 0
		.amdhsa_private_segment_fixed_size 0
		.amdhsa_kernarg_size 496
		.amdhsa_user_sgpr_count 2
		.amdhsa_user_sgpr_dispatch_ptr 0
		.amdhsa_user_sgpr_queue_ptr 0
		.amdhsa_user_sgpr_kernarg_segment_ptr 1
		.amdhsa_user_sgpr_dispatch_id 0
		.amdhsa_user_sgpr_kernarg_preload_length 0
		.amdhsa_user_sgpr_kernarg_preload_offset 0
		.amdhsa_user_sgpr_private_segment_size 0
		.amdhsa_uses_dynamic_stack 0
		.amdhsa_enable_private_segment 0
		.amdhsa_system_sgpr_workgroup_id_x 1
		.amdhsa_system_sgpr_workgroup_id_y 0
		.amdhsa_system_sgpr_workgroup_id_z 0
		.amdhsa_system_sgpr_workgroup_info 0
		.amdhsa_system_vgpr_workitem_id 2
		.amdhsa_next_free_vgpr 256
		.amdhsa_next_free_sgpr 98
		.amdhsa_accum_offset 256
		.amdhsa_reserve_vcc 1
		.amdhsa_float_round_mode_32 0
		.amdhsa_float_round_mode_16_64 0
		.amdhsa_float_denorm_mode_32 3
		.amdhsa_float_denorm_mode_16_64 3
		.amdhsa_dx10_clamp 1
		.amdhsa_ieee_mode 1
		.amdhsa_fp16_overflow 0
		.amdhsa_tg_split 0
		.amdhsa_exception_fp_ieee_invalid_op 0
		.amdhsa_exception_fp_denorm_src 0
		.amdhsa_exception_fp_ieee_div_zero 0
		.amdhsa_exception_fp_ieee_overflow 0
		.amdhsa_exception_fp_ieee_underflow 0
		.amdhsa_exception_fp_ieee_inexact 0
		.amdhsa_exception_int_div_zero 0
	.end_amdhsa_kernel

; #define LAS __attribute__((address_space(3)))
; __global__ void __launch_bounds__(512, 2) fwd_kernel(Args args) {
;     extern __shared__ __attribute__((aligned(16))) unsigned char lds_raw[];
;     LAS unsigned char* lds = (LAS unsigned char*)lds_raw;
;     cg::grid_group grid = cg::this_grid();
;     const int tid = threadIdx.x, lane = tid & 63, wave = __builtin_amdgcn_readfirstlane(tid >> 6);
amdhsa.kernels:
  - .agpr_count:     0
    .args:
      - .offset:         0
        .size:           240
        .value_kind:     by_value
      - .offset:         240
        .size:           4
        .value_kind:     hidden_block_count_x
      - .offset:         244
        .size:           4
        .value_kind:     hidden_block_count_y
      - .offset:         248
        .size:           4
        .value_kind:     hidden_block_count_z
      - .offset:         252
        .size:           2
        .value_kind:     hidden_group_size_x
      - .offset:         254
        .size:           2
        .value_kind:     hidden_group_size_y
      - .offset:         256
        .size:           2
        .value_kind:     hidden_group_size_z
      - .offset:         258
        .size:           2
        .value_kind:     hidden_remainder_x
      - .offset:         260
        .size:           2
        .value_kind:     hidden_remainder_y
      - .offset:         262
        .size:           2
        .value_kind:     hidden_remainder_z
      - .offset:         280
        .size:           8
        .value_kind:     hidden_global_offset_x
      - .offset:         288
        .size:           8
        .value_kind:     hidden_global_offset_y
      - .offset:         296
        .size:           8
        .value_kind:     hidden_global_offset_z
      - .offset:         304
        .size:           2
        .value_kind:     hidden_grid_dims
      - .offset:         328
        .size:           8
        .value_kind:     hidden_multigrid_sync_arg
      - .offset:         360
        .size:           4
        .value_kind:     hidden_dynamic_lds_size
    .group_segment_fixed_size: 0
    .kernarg_segment_align: 8
    .kernarg_segment_size: 496
    .language:       OpenCL C
    .language_version:
      - 2
      - 0
    .max_flat_workgroup_size: 512
    .name:           _Z10fwd_kernel4Args
    .private_segment_fixed_size: 0
    .sgpr_count:     104
    .sgpr_spill_count: 74
    .symbol:         _Z10fwd_kernel4Args.kd
    .uniform_work_group_size: 1
    .uses_dynamic_stack: false
    .vgpr_count:     256
    .vgpr_spill_count: 0
    .wavefront_size: 64
